# GEMM K-loops without s_setprio toggles + P1 norm next-row prefetch + mods_phase 32 loads in flight
# speedup vs baseline: 1.0050x; 1.0008x over previous
.LBB0_213:
	s_add_u32 s20, s18, 0xfffc0080
	s_addc_u32 s21, s19, -1
	s_add_i32 s48, 0, 0x10000
	s_cmp_eq_u32 s46, 12
	s_cselect_b32 s23, s11, s21
	s_cselect_b32 s22, s42, s20
	s_cselect_b32 s21, s9, s45
	s_cselect_b32 s20, s43, s44
	s_add_i32 s50, 0, 0x14000
	v_add_u32_e32 v156, s48, v141
	v_add_u32_e32 v172, s50, v141
	ds_read_b128 v[144:147], v156
	ds_read_b128 v[148:151], v156 offset:1024
	ds_read_b128 v[152:155], v156 offset:2048
	ds_read_b128 v[156:159], v156 offset:3072
	ds_read_b128 v[160:163], v172
	ds_read_b128 v[164:167], v172 offset:1024
	ds_read_b128 v[168:171], v172 offset:2048
	ds_read_b128 v[172:175], v172 offset:3072
	v_lshl_add_u64 v[180:181], s[18:19], 0, v[136:137]
	s_add_i32 m0, s29, 0xc000
	ds_read_b128 v[176:179], v143
	ds_read_b128 v[186:189], v143 offset:1024
	ds_read_b128 v[190:193], v143 offset:2048
	ds_read_b128 v[212:215], v143 offset:3072
	ds_read_b128 v[216:219], v143 offset:4096
	ds_read_b128 v[220:223], v143 offset:5120
	ds_read_b128 v[224:227], v143 offset:6144
	ds_read_b128 v[228:231], v143 offset:7168
	global_load_lds_dwordx4 v[180:181], off
	v_lshl_add_u64 v[180:181], s[18:19], 0, v[138:139]
	s_add_i32 m0, s29, 0xe000
	s_nop 0
	global_load_lds_dwordx4 v[180:181], off
	s_waitcnt vmcnt(8)
	s_waitcnt lgkmcnt(0)
	s_barrier
	s_waitcnt lgkmcnt(0)
	v_mfma_f32_16x16x32_bf16 v[126:129], v[144:147], v[176:179], v[126:129]
	v_mfma_f32_16x16x32_bf16 v[122:125], v[152:155], v[176:179], v[122:125]
	v_mfma_f32_16x16x32_bf16 v[118:121], v[144:147], v[190:193], v[118:121]
	v_mfma_f32_16x16x32_bf16 v[114:117], v[152:155], v[190:193], v[114:117]
	v_mfma_f32_16x16x32_bf16 v[102:105], v[144:147], v[216:219], v[102:105]
	v_mfma_f32_16x16x32_bf16 v[98:101], v[152:155], v[216:219], v[98:101]
	v_mfma_f32_16x16x32_bf16 v[86:89], v[144:147], v[224:227], v[86:89]
	v_mfma_f32_16x16x32_bf16 v[82:85], v[152:155], v[224:227], v[82:85]
	v_mfma_f32_16x16x32_bf16 v[126:129], v[148:151], v[186:189], v[126:129]
	v_mfma_f32_16x16x32_bf16 v[122:125], v[156:159], v[186:189], v[122:125]
	v_mfma_f32_16x16x32_bf16 v[118:121], v[148:151], v[212:215], v[118:121]
	v_mfma_f32_16x16x32_bf16 v[114:117], v[156:159], v[212:215], v[114:117]
	v_mfma_f32_16x16x32_bf16 v[102:105], v[148:151], v[220:223], v[102:105]
	v_mfma_f32_16x16x32_bf16 v[98:101], v[156:159], v[220:223], v[98:101]
	v_mfma_f32_16x16x32_bf16 v[86:89], v[148:151], v[228:231], v[86:89]
	v_mfma_f32_16x16x32_bf16 v[82:85], v[156:159], v[228:231], v[82:85]
	v_mfma_f32_16x16x32_bf16 v[110:113], v[160:163], v[176:179], v[110:113]
	v_mfma_f32_16x16x32_bf16 v[106:109], v[168:171], v[176:179], v[106:109]
	v_mfma_f32_16x16x32_bf16 v[94:97], v[160:163], v[190:193], v[94:97]
	v_mfma_f32_16x16x32_bf16 v[90:93], v[168:171], v[190:193], v[90:93]
	v_mfma_f32_16x16x32_bf16 v[78:81], v[160:163], v[216:219], v[78:81]
	v_mfma_f32_16x16x32_bf16 v[74:77], v[168:171], v[216:219], v[74:77]
	v_mfma_f32_16x16x32_bf16 v[70:73], v[160:163], v[224:227], v[70:73]
	v_mfma_f32_16x16x32_bf16 v[66:69], v[168:171], v[224:227], v[66:69]
	v_mfma_f32_16x16x32_bf16 v[110:113], v[164:167], v[186:189], v[110:113]
	v_mfma_f32_16x16x32_bf16 v[106:109], v[172:175], v[186:189], v[106:109]
	v_mfma_f32_16x16x32_bf16 v[94:97], v[164:167], v[212:215], v[94:97]
	v_mfma_f32_16x16x32_bf16 v[90:93], v[172:175], v[212:215], v[90:93]
	v_mfma_f32_16x16x32_bf16 v[78:81], v[164:167], v[220:223], v[78:81]
	v_mfma_f32_16x16x32_bf16 v[74:77], v[172:175], v[220:223], v[74:77]
	v_mfma_f32_16x16x32_bf16 v[70:73], v[164:167], v[228:231], v[70:73]
	v_mfma_f32_16x16x32_bf16 v[66:69], v[172:175], v[228:231], v[66:69]
	s_barrier
	s_add_i32 s48, s48, s28
	v_lshl_add_u64 v[180:181], s[20:21], 0, v[0:1]
	s_mov_b32 m0, s48
	ds_read_b128 v[176:179], v143 offset:16384
	ds_read_b128 v[186:189], v143 offset:17408
	ds_read_b128 v[190:193], v143 offset:18432
	ds_read_b128 v[212:215], v143 offset:19456
	ds_read_b128 v[216:219], v143 offset:20480
	ds_read_b128 v[220:223], v143 offset:21504
	ds_read_b128 v[224:227], v143 offset:22528
	ds_read_b128 v[228:231], v143 offset:23552
	global_load_lds_dwordx4 v[180:181], off
	s_add_i32 m0, s48, 0x2000
	s_add_u32 s48, s20, 0x40000
	v_lshl_add_u64 v[194:195], s[20:21], 0, v[130:131]
	s_addc_u32 s49, s21, 0
	s_add_i32 s50, s50, s28
	global_load_lds_dwordx4 v[194:195], off
	v_lshl_add_u64 v[232:233], s[48:49], 0, v[0:1]
	s_mov_b32 m0, s50
	v_lshl_add_u64 v[234:235], s[22:23], 0, v[132:133]
	global_load_lds_dwordx4 v[232:233], off
	v_lshl_add_u64 v[232:233], s[48:49], 0, v[130:131]
	s_add_i32 m0, s50, 0x2000
	s_nop 0
	global_load_lds_dwordx4 v[232:233], off
	v_lshl_add_u64 v[232:233], s[22:23], 0, v[134:135]
	s_mov_b32 m0, s29
	s_nop 0
	global_load_lds_dwordx4 v[232:233], off
	s_mov_b32 m0, s30
	s_nop 0
	global_load_lds_dwordx4 v[234:235], off
	s_waitcnt vmcnt(8)
	s_waitcnt lgkmcnt(0)
	s_barrier
	s_waitcnt lgkmcnt(0)
	v_mfma_f32_16x16x32_bf16 v[62:65], v[144:147], v[176:179], v[62:65]
	v_mfma_f32_16x16x32_bf16 v[58:61], v[152:155], v[176:179], v[58:61]
	v_mfma_f32_16x16x32_bf16 v[54:57], v[144:147], v[190:193], v[54:57]
	v_mfma_f32_16x16x32_bf16 v[50:53], v[152:155], v[190:193], v[50:53]
	v_mfma_f32_16x16x32_bf16 v[38:41], v[144:147], v[216:219], v[38:41]
	v_mfma_f32_16x16x32_bf16 v[34:37], v[152:155], v[216:219], v[34:37]
	v_mfma_f32_16x16x32_bf16 v[22:25], v[144:147], v[224:227], v[22:25]
	v_mfma_f32_16x16x32_bf16 v[18:21], v[152:155], v[224:227], v[18:21]
	v_mfma_f32_16x16x32_bf16 v[62:65], v[148:151], v[186:189], v[62:65]
	v_mfma_f32_16x16x32_bf16 v[58:61], v[156:159], v[186:189], v[58:61]
	v_mfma_f32_16x16x32_bf16 v[54:57], v[148:151], v[212:215], v[54:57]
	v_mfma_f32_16x16x32_bf16 v[50:53], v[156:159], v[212:215], v[50:53]
	v_mfma_f32_16x16x32_bf16 v[38:41], v[148:151], v[220:223], v[38:41]
	v_mfma_f32_16x16x32_bf16 v[34:37], v[156:159], v[220:223], v[34:37]
	v_mfma_f32_16x16x32_bf16 v[22:25], v[148:151], v[228:231], v[22:25]
	v_mfma_f32_16x16x32_bf16 v[18:21], v[156:159], v[228:231], v[18:21]
	v_mfma_f32_16x16x32_bf16 v[46:49], v[160:163], v[176:179], v[46:49]
	v_mfma_f32_16x16x32_bf16 v[42:45], v[168:171], v[176:179], v[42:45]
	v_mfma_f32_16x16x32_bf16 v[30:33], v[160:163], v[190:193], v[30:33]
	v_mfma_f32_16x16x32_bf16 v[26:29], v[168:171], v[190:193], v[26:29]
	v_mfma_f32_16x16x32_bf16 v[14:17], v[160:163], v[216:219], v[14:17]
	v_mfma_f32_16x16x32_bf16 v[10:13], v[168:171], v[216:219], v[10:13]
	v_mfma_f32_16x16x32_bf16 v[6:9], v[160:163], v[224:227], v[6:9]
	v_mfma_f32_16x16x32_bf16 v[2:5], v[168:171], v[224:227], v[2:5]
	v_mfma_f32_16x16x32_bf16 v[46:49], v[164:167], v[186:189], v[46:49]
	v_mfma_f32_16x16x32_bf16 v[42:45], v[172:175], v[186:189], v[42:45]
	v_mfma_f32_16x16x32_bf16 v[30:33], v[164:167], v[212:215], v[30:33]
	v_mfma_f32_16x16x32_bf16 v[26:29], v[172:175], v[212:215], v[26:29]
	v_mfma_f32_16x16x32_bf16 v[14:17], v[164:167], v[220:223], v[14:17]
	v_mfma_f32_16x16x32_bf16 v[10:13], v[172:175], v[220:223], v[10:13]
	v_mfma_f32_16x16x32_bf16 v[6:9], v[164:167], v[228:231], v[6:9]
	v_mfma_f32_16x16x32_bf16 v[2:5], v[172:175], v[228:231], v[2:5]
	s_barrier
	s_add_i32 s48, 0, 0x18000
	s_add_i32 s49, 0, 0x1c000
	v_add_u32_e32 v156, s48, v141
	v_add_u32_e32 v172, s49, v141
	ds_read_b128 v[144:147], v156
	ds_read_b128 v[148:151], v156 offset:1024
	ds_read_b128 v[152:155], v156 offset:2048
	ds_read_b128 v[156:159], v156 offset:3072
	ds_read_b128 v[160:163], v172
	ds_read_b128 v[164:167], v172 offset:1024
	ds_read_b128 v[168:171], v172 offset:2048
	ds_read_b128 v[172:175], v172 offset:3072
	s_add_u32 s22, s22, 0x40000
	s_addc_u32 s23, s23, 0
	s_mov_b32 m0, s31
	v_lshl_add_u64 v[236:237], s[22:23], 0, v[134:135]
	ds_read_b128 v[176:179], v143 offset:32768
	ds_read_b128 v[186:189], v143 offset:33792
	ds_read_b128 v[190:193], v143 offset:34816
	ds_read_b128 v[212:215], v143 offset:35840
	ds_read_b128 v[216:219], v143 offset:36864
	ds_read_b128 v[220:223], v143 offset:37888
	ds_read_b128 v[224:227], v143 offset:38912
	ds_read_b128 v[228:231], v143 offset:39936
	global_load_lds_dwordx4 v[236:237], off
	v_lshl_add_u64 v[236:237], s[22:23], 0, v[132:133]
	s_mov_b32 m0, s34
	s_nop 0
	global_load_lds_dwordx4 v[236:237], off
	s_waitcnt vmcnt(8)
	s_waitcnt lgkmcnt(0)
	s_barrier
	s_waitcnt lgkmcnt(0)
	v_mfma_f32_16x16x32_bf16 v[126:129], v[144:147], v[176:179], v[126:129]
	v_mfma_f32_16x16x32_bf16 v[122:125], v[152:155], v[176:179], v[122:125]
	v_mfma_f32_16x16x32_bf16 v[118:121], v[144:147], v[190:193], v[118:121]
	v_mfma_f32_16x16x32_bf16 v[114:117], v[152:155], v[190:193], v[114:117]
	v_mfma_f32_16x16x32_bf16 v[102:105], v[144:147], v[216:219], v[102:105]
	v_mfma_f32_16x16x32_bf16 v[98:101], v[152:155], v[216:219], v[98:101]
	v_mfma_f32_16x16x32_bf16 v[86:89], v[144:147], v[224:227], v[86:89]
	v_mfma_f32_16x16x32_bf16 v[82:85], v[152:155], v[224:227], v[82:85]
	v_mfma_f32_16x16x32_bf16 v[126:129], v[148:151], v[186:189], v[126:129]
	v_mfma_f32_16x16x32_bf16 v[122:125], v[156:159], v[186:189], v[122:125]
	v_mfma_f32_16x16x32_bf16 v[118:121], v[148:151], v[212:215], v[118:121]
	v_mfma_f32_16x16x32_bf16 v[114:117], v[156:159], v[212:215], v[114:117]
	v_mfma_f32_16x16x32_bf16 v[102:105], v[148:151], v[220:223], v[102:105]
	v_mfma_f32_16x16x32_bf16 v[98:101], v[156:159], v[220:223], v[98:101]
	v_mfma_f32_16x16x32_bf16 v[86:89], v[148:151], v[228:231], v[86:89]
	v_mfma_f32_16x16x32_bf16 v[82:85], v[156:159], v[228:231], v[82:85]
	v_mfma_f32_16x16x32_bf16 v[110:113], v[160:163], v[176:179], v[110:113]
	v_mfma_f32_16x16x32_bf16 v[106:109], v[168:171], v[176:179], v[106:109]
	v_mfma_f32_16x16x32_bf16 v[94:97], v[160:163], v[190:193], v[94:97]
	v_mfma_f32_16x16x32_bf16 v[90:93], v[168:171], v[190:193], v[90:93]
	v_mfma_f32_16x16x32_bf16 v[78:81], v[160:163], v[216:219], v[78:81]
	v_mfma_f32_16x16x32_bf16 v[74:77], v[168:171], v[216:219], v[74:77]
	v_mfma_f32_16x16x32_bf16 v[70:73], v[160:163], v[224:227], v[70:73]
	v_mfma_f32_16x16x32_bf16 v[66:69], v[168:171], v[224:227], v[66:69]
	v_mfma_f32_16x16x32_bf16 v[110:113], v[164:167], v[186:189], v[110:113]
	v_mfma_f32_16x16x32_bf16 v[106:109], v[172:175], v[186:189], v[106:109]
	v_mfma_f32_16x16x32_bf16 v[94:97], v[164:167], v[212:215], v[94:97]
	v_mfma_f32_16x16x32_bf16 v[90:93], v[172:175], v[212:215], v[90:93]
	v_mfma_f32_16x16x32_bf16 v[78:81], v[164:167], v[220:223], v[78:81]
	v_mfma_f32_16x16x32_bf16 v[74:77], v[172:175], v[220:223], v[74:77]
	v_mfma_f32_16x16x32_bf16 v[70:73], v[164:167], v[228:231], v[70:73]
	v_mfma_f32_16x16x32_bf16 v[66:69], v[172:175], v[228:231], v[66:69]
	s_barrier
	s_add_i32 s22, s48, s28
	v_lshl_add_u64 v[180:181], v[180:181], 0, s[16:17]
	s_mov_b32 m0, s22
	ds_read_b128 v[176:179], v143 offset:49152
	ds_read_b128 v[186:189], v143 offset:50176
	ds_read_b128 v[190:193], v143 offset:51200
	ds_read_b128 v[212:215], v143 offset:52224
	ds_read_b128 v[216:219], v143 offset:53248
	ds_read_b128 v[220:223], v143 offset:54272
	ds_read_b128 v[224:227], v143 offset:55296
	ds_read_b128 v[228:231], v143 offset:56320
	global_load_lds_dwordx4 v[180:181], off
	s_add_i32 m0, s22, 0x2000
	s_add_u32 s20, s20, 0x40080
	v_lshl_add_u64 v[180:181], v[194:195], 0, s[16:17]
	s_addc_u32 s21, s21, 0
	s_add_i32 s22, s49, s28
	global_load_lds_dwordx4 v[180:181], off
	v_lshl_add_u64 v[180:181], s[20:21], 0, v[0:1]
	s_mov_b32 m0, s22
	s_nop 0
	global_load_lds_dwordx4 v[180:181], off
	v_lshl_add_u64 v[180:181], s[20:21], 0, v[130:131]
	s_add_i32 m0, s22, 0x2000
	s_nop 0
	global_load_lds_dwordx4 v[180:181], off
	v_lshl_add_u64 v[180:181], v[232:233], 0, s[16:17]
	s_mov_b32 m0, s35
	s_nop 0
	global_load_lds_dwordx4 v[180:181], off
	v_lshl_add_u64 v[180:181], v[234:235], 0, s[16:17]
	s_mov_b32 m0, s36
	s_nop 0
	global_load_lds_dwordx4 v[180:181], off
	s_waitcnt vmcnt(8)
	s_waitcnt lgkmcnt(0)
	s_barrier
	s_waitcnt lgkmcnt(0)
	v_mfma_f32_16x16x32_bf16 v[62:65], v[144:147], v[176:179], v[62:65]
	v_mfma_f32_16x16x32_bf16 v[58:61], v[152:155], v[176:179], v[58:61]
	v_mfma_f32_16x16x32_bf16 v[54:57], v[144:147], v[190:193], v[54:57]
	v_mfma_f32_16x16x32_bf16 v[50:53], v[152:155], v[190:193], v[50:53]
	v_mfma_f32_16x16x32_bf16 v[38:41], v[144:147], v[216:219], v[38:41]
	v_mfma_f32_16x16x32_bf16 v[34:37], v[152:155], v[216:219], v[34:37]
	v_mfma_f32_16x16x32_bf16 v[22:25], v[144:147], v[224:227], v[22:25]
	v_mfma_f32_16x16x32_bf16 v[18:21], v[152:155], v[224:227], v[18:21]
	v_mfma_f32_16x16x32_bf16 v[62:65], v[148:151], v[186:189], v[62:65]
	v_mfma_f32_16x16x32_bf16 v[58:61], v[156:159], v[186:189], v[58:61]
	v_mfma_f32_16x16x32_bf16 v[54:57], v[148:151], v[212:215], v[54:57]
	v_mfma_f32_16x16x32_bf16 v[50:53], v[156:159], v[212:215], v[50:53]
	v_mfma_f32_16x16x32_bf16 v[38:41], v[148:151], v[220:223], v[38:41]
	v_mfma_f32_16x16x32_bf16 v[34:37], v[156:159], v[220:223], v[34:37]
	v_mfma_f32_16x16x32_bf16 v[22:25], v[148:151], v[228:231], v[22:25]
	v_mfma_f32_16x16x32_bf16 v[18:21], v[156:159], v[228:231], v[18:21]
	v_mfma_f32_16x16x32_bf16 v[46:49], v[160:163], v[176:179], v[46:49]
	v_mfma_f32_16x16x32_bf16 v[42:45], v[168:171], v[176:179], v[42:45]
	v_mfma_f32_16x16x32_bf16 v[30:33], v[160:163], v[190:193], v[30:33]
	v_mfma_f32_16x16x32_bf16 v[26:29], v[168:171], v[190:193], v[26:29]
	v_mfma_f32_16x16x32_bf16 v[14:17], v[160:163], v[216:219], v[14:17]
	v_mfma_f32_16x16x32_bf16 v[10:13], v[168:171], v[216:219], v[10:13]
	v_mfma_f32_16x16x32_bf16 v[6:9], v[160:163], v[224:227], v[6:9]
	v_mfma_f32_16x16x32_bf16 v[2:5], v[168:171], v[224:227], v[2:5]
	v_mfma_f32_16x16x32_bf16 v[46:49], v[164:167], v[186:189], v[46:49]
	v_mfma_f32_16x16x32_bf16 v[42:45], v[172:175], v[186:189], v[42:45]
	v_mfma_f32_16x16x32_bf16 v[30:33], v[164:167], v[212:215], v[30:33]
	v_mfma_f32_16x16x32_bf16 v[26:29], v[172:175], v[212:215], v[26:29]
	v_mfma_f32_16x16x32_bf16 v[14:17], v[164:167], v[220:223], v[14:17]
	v_mfma_f32_16x16x32_bf16 v[10:13], v[172:175], v[220:223], v[10:13]
	v_mfma_f32_16x16x32_bf16 v[6:9], v[164:167], v[228:231], v[6:9]
	v_mfma_f32_16x16x32_bf16 v[2:5], v[172:175], v[228:231], v[2:5]
	s_barrier
	s_add_i32 s46, s46, 2
	s_add_u32 s18, s18, 0x100
	s_addc_u32 s19, s19, 0
	s_add_u32 s44, s44, 0x100
	s_addc_u32 s45, s45, 0
	s_cmp_gt_u32 s46, 13
	s_cbranch_scc0 .LBB0_213
	s_and_b64 vcc, exec, s[6:7]
	s_cbranch_vccz .LBB0_216
	s_barrier

.LBB0_684:
	s_add_u32 s22, s20, 0xfffc0080
	s_addc_u32 s23, s21, -1
	s_add_i32 s53, 0, 0x10000
	s_cmp_eq_u32 s52, 12
	s_cselect_b32 s25, s11, s23
	s_cselect_b32 s24, s48, s22
	s_cselect_b32 s23, s9, s51
	s_cselect_b32 s22, s49, s50
	s_add_i32 s56, 0, 0x14000
	v_add_u32_e32 v156, s53, v145
	v_add_u32_e32 v172, s56, v145
	ds_read_b128 v[140:143], v156
	ds_read_b128 v[148:151], v156 offset:1024
	ds_read_b128 v[152:155], v156 offset:2048
	ds_read_b128 v[156:159], v156 offset:3072
	ds_read_b128 v[160:163], v172
	ds_read_b128 v[164:167], v172 offset:1024
	ds_read_b128 v[168:171], v172 offset:2048
	ds_read_b128 v[172:175], v172 offset:3072
	v_lshl_add_u64 v[180:181], s[20:21], 0, v[136:137]
	s_add_i32 m0, s35, 0xc000
	ds_read_b128 v[176:179], v147
	ds_read_b128 v[186:189], v147 offset:1024
	ds_read_b128 v[190:193], v147 offset:2048
	ds_read_b128 v[212:215], v147 offset:3072
	ds_read_b128 v[216:219], v147 offset:4096
	ds_read_b128 v[220:223], v147 offset:5120
	ds_read_b128 v[224:227], v147 offset:6144
	ds_read_b128 v[228:231], v147 offset:7168
	global_load_lds_dwordx4 v[180:181], off
	v_lshl_add_u64 v[180:181], s[20:21], 0, v[138:139]
	s_add_i32 m0, s35, 0xe000
	s_nop 0
	global_load_lds_dwordx4 v[180:181], off
	s_waitcnt vmcnt(8)
	s_waitcnt lgkmcnt(0)
	s_barrier
	s_waitcnt lgkmcnt(0)
	v_mfma_f32_16x16x32_bf16 v[126:129], v[140:143], v[176:179], v[126:129]
	v_mfma_f32_16x16x32_bf16 v[122:125], v[152:155], v[176:179], v[122:125]
	v_mfma_f32_16x16x32_bf16 v[110:113], v[140:143], v[190:193], v[110:113]
	v_mfma_f32_16x16x32_bf16 v[106:109], v[152:155], v[190:193], v[106:109]
	v_mfma_f32_16x16x32_bf16 v[94:97], v[140:143], v[216:219], v[94:97]
	v_mfma_f32_16x16x32_bf16 v[90:93], v[152:155], v[216:219], v[90:93]
	v_mfma_f32_16x16x32_bf16 v[78:81], v[140:143], v[224:227], v[78:81]
	v_mfma_f32_16x16x32_bf16 v[74:77], v[152:155], v[224:227], v[74:77]
	v_mfma_f32_16x16x32_bf16 v[126:129], v[148:151], v[186:189], v[126:129]
	v_mfma_f32_16x16x32_bf16 v[122:125], v[156:159], v[186:189], v[122:125]
	v_mfma_f32_16x16x32_bf16 v[110:113], v[148:151], v[212:215], v[110:113]
	v_mfma_f32_16x16x32_bf16 v[106:109], v[156:159], v[212:215], v[106:109]
	v_mfma_f32_16x16x32_bf16 v[94:97], v[148:151], v[220:223], v[94:97]
	v_mfma_f32_16x16x32_bf16 v[90:93], v[156:159], v[220:223], v[90:93]
	v_mfma_f32_16x16x32_bf16 v[78:81], v[148:151], v[228:231], v[78:81]
	v_mfma_f32_16x16x32_bf16 v[74:77], v[156:159], v[228:231], v[74:77]
	v_mfma_f32_16x16x32_bf16 v[118:121], v[160:163], v[176:179], v[118:121]
	v_mfma_f32_16x16x32_bf16 v[114:117], v[168:171], v[176:179], v[114:117]
	v_mfma_f32_16x16x32_bf16 v[102:105], v[160:163], v[190:193], v[102:105]
	v_mfma_f32_16x16x32_bf16 v[98:101], v[168:171], v[190:193], v[98:101]
	v_mfma_f32_16x16x32_bf16 v[86:89], v[160:163], v[216:219], v[86:89]
	v_mfma_f32_16x16x32_bf16 v[82:85], v[168:171], v[216:219], v[82:85]
	v_mfma_f32_16x16x32_bf16 v[70:73], v[160:163], v[224:227], v[70:73]
	v_mfma_f32_16x16x32_bf16 v[66:69], v[168:171], v[224:227], v[66:69]
	v_mfma_f32_16x16x32_bf16 v[118:121], v[164:167], v[186:189], v[118:121]
	v_mfma_f32_16x16x32_bf16 v[114:117], v[172:175], v[186:189], v[114:117]
	v_mfma_f32_16x16x32_bf16 v[102:105], v[164:167], v[212:215], v[102:105]
	v_mfma_f32_16x16x32_bf16 v[98:101], v[172:175], v[212:215], v[98:101]
	v_mfma_f32_16x16x32_bf16 v[86:89], v[164:167], v[220:223], v[86:89]
	v_mfma_f32_16x16x32_bf16 v[82:85], v[172:175], v[220:223], v[82:85]
	v_mfma_f32_16x16x32_bf16 v[70:73], v[164:167], v[228:231], v[70:73]
	v_mfma_f32_16x16x32_bf16 v[66:69], v[172:175], v[228:231], v[66:69]
	s_barrier
	s_add_i32 s53, s53, s31
	v_lshl_add_u64 v[180:181], s[22:23], 0, v[0:1]
	s_mov_b32 m0, s53
	ds_read_b128 v[176:179], v147 offset:16384
	ds_read_b128 v[186:189], v147 offset:17408
	ds_read_b128 v[190:193], v147 offset:18432
	ds_read_b128 v[212:215], v147 offset:19456
	ds_read_b128 v[216:219], v147 offset:20480
	ds_read_b128 v[220:223], v147 offset:21504
	ds_read_b128 v[224:227], v147 offset:22528
	ds_read_b128 v[228:231], v147 offset:23552
	global_load_lds_dwordx4 v[180:181], off
	s_add_i32 m0, s53, 0x2000
	s_add_u32 s54, s22, 0x40000
	v_lshl_add_u64 v[194:195], s[22:23], 0, v[134:135]
	s_addc_u32 s55, s23, 0
	s_add_i32 s53, s56, s31
	global_load_lds_dwordx4 v[194:195], off
	v_lshl_add_u64 v[232:233], s[54:55], 0, v[0:1]
	s_mov_b32 m0, s53
	v_lshl_add_u64 v[234:235], s[24:25], 0, v[132:133]
	global_load_lds_dwordx4 v[232:233], off
	v_lshl_add_u64 v[232:233], s[54:55], 0, v[134:135]
	s_add_i32 m0, s53, 0x2000
	s_nop 0
	global_load_lds_dwordx4 v[232:233], off
	v_lshl_add_u64 v[232:233], s[24:25], 0, v[130:131]
	s_mov_b32 m0, s35
	s_nop 0
	global_load_lds_dwordx4 v[232:233], off
	s_mov_b32 m0, s36
	s_nop 0
	global_load_lds_dwordx4 v[234:235], off
	s_waitcnt vmcnt(8)
	s_waitcnt lgkmcnt(0)
	s_barrier
	s_waitcnt lgkmcnt(0)
	v_mfma_f32_16x16x32_bf16 v[62:65], v[140:143], v[176:179], v[62:65]
	v_mfma_f32_16x16x32_bf16 v[58:61], v[152:155], v[176:179], v[58:61]
	v_mfma_f32_16x16x32_bf16 v[46:49], v[140:143], v[190:193], v[46:49]
	v_mfma_f32_16x16x32_bf16 v[42:45], v[152:155], v[190:193], v[42:45]
	v_mfma_f32_16x16x32_bf16 v[30:33], v[140:143], v[216:219], v[30:33]
	v_mfma_f32_16x16x32_bf16 v[26:29], v[152:155], v[216:219], v[26:29]
	v_mfma_f32_16x16x32_bf16 v[14:17], v[140:143], v[224:227], v[14:17]
	v_mfma_f32_16x16x32_bf16 v[10:13], v[152:155], v[224:227], v[10:13]
	v_mfma_f32_16x16x32_bf16 v[62:65], v[148:151], v[186:189], v[62:65]
	v_mfma_f32_16x16x32_bf16 v[58:61], v[156:159], v[186:189], v[58:61]
	v_mfma_f32_16x16x32_bf16 v[46:49], v[148:151], v[212:215], v[46:49]
	v_mfma_f32_16x16x32_bf16 v[42:45], v[156:159], v[212:215], v[42:45]
	v_mfma_f32_16x16x32_bf16 v[30:33], v[148:151], v[220:223], v[30:33]
	v_mfma_f32_16x16x32_bf16 v[26:29], v[156:159], v[220:223], v[26:29]
	v_mfma_f32_16x16x32_bf16 v[14:17], v[148:151], v[228:231], v[14:17]
	v_mfma_f32_16x16x32_bf16 v[10:13], v[156:159], v[228:231], v[10:13]
	v_mfma_f32_16x16x32_bf16 v[54:57], v[160:163], v[176:179], v[54:57]
	v_mfma_f32_16x16x32_bf16 v[50:53], v[168:171], v[176:179], v[50:53]
	v_mfma_f32_16x16x32_bf16 v[38:41], v[160:163], v[190:193], v[38:41]
	v_mfma_f32_16x16x32_bf16 v[34:37], v[168:171], v[190:193], v[34:37]
	v_mfma_f32_16x16x32_bf16 v[22:25], v[160:163], v[216:219], v[22:25]
	v_mfma_f32_16x16x32_bf16 v[18:21], v[168:171], v[216:219], v[18:21]
	v_mfma_f32_16x16x32_bf16 v[6:9], v[160:163], v[224:227], v[6:9]
	v_mfma_f32_16x16x32_bf16 v[2:5], v[168:171], v[224:227], v[2:5]
	v_mfma_f32_16x16x32_bf16 v[54:57], v[164:167], v[186:189], v[54:57]
	v_mfma_f32_16x16x32_bf16 v[50:53], v[172:175], v[186:189], v[50:53]
	v_mfma_f32_16x16x32_bf16 v[38:41], v[164:167], v[212:215], v[38:41]
	v_mfma_f32_16x16x32_bf16 v[34:37], v[172:175], v[212:215], v[34:37]
	v_mfma_f32_16x16x32_bf16 v[22:25], v[164:167], v[220:223], v[22:25]
	v_mfma_f32_16x16x32_bf16 v[18:21], v[172:175], v[220:223], v[18:21]
	v_mfma_f32_16x16x32_bf16 v[6:9], v[164:167], v[228:231], v[6:9]
	v_mfma_f32_16x16x32_bf16 v[2:5], v[172:175], v[228:231], v[2:5]
	s_barrier
	s_add_i32 s53, 0, 0x18000
	s_add_i32 s54, 0, 0x1c000
	v_add_u32_e32 v156, s53, v145
	v_add_u32_e32 v172, s54, v145
	ds_read_b128 v[140:143], v156
	ds_read_b128 v[148:151], v156 offset:1024
	ds_read_b128 v[152:155], v156 offset:2048
	ds_read_b128 v[156:159], v156 offset:3072
	ds_read_b128 v[160:163], v172
	ds_read_b128 v[164:167], v172 offset:1024
	ds_read_b128 v[168:171], v172 offset:2048
	ds_read_b128 v[172:175], v172 offset:3072
	s_add_u32 s24, s24, 0x40000
	s_addc_u32 s25, s25, 0
	s_mov_b32 m0, s37
	v_lshl_add_u64 v[236:237], s[24:25], 0, v[130:131]
	ds_read_b128 v[176:179], v147 offset:32768
	ds_read_b128 v[186:189], v147 offset:33792
	ds_read_b128 v[190:193], v147 offset:34816
	ds_read_b128 v[212:215], v147 offset:35840
	ds_read_b128 v[216:219], v147 offset:36864
	ds_read_b128 v[220:223], v147 offset:37888
	ds_read_b128 v[224:227], v147 offset:38912
	ds_read_b128 v[228:231], v147 offset:39936
	global_load_lds_dwordx4 v[236:237], off
	v_lshl_add_u64 v[236:237], s[24:25], 0, v[132:133]
	s_mov_b32 m0, s42
	s_nop 0
	global_load_lds_dwordx4 v[236:237], off
	s_waitcnt vmcnt(8)
	s_waitcnt lgkmcnt(0)
	s_barrier
	s_waitcnt lgkmcnt(0)
	v_mfma_f32_16x16x32_bf16 v[126:129], v[140:143], v[176:179], v[126:129]
	v_mfma_f32_16x16x32_bf16 v[122:125], v[152:155], v[176:179], v[122:125]
	v_mfma_f32_16x16x32_bf16 v[110:113], v[140:143], v[190:193], v[110:113]
	v_mfma_f32_16x16x32_bf16 v[106:109], v[152:155], v[190:193], v[106:109]
	v_mfma_f32_16x16x32_bf16 v[94:97], v[140:143], v[216:219], v[94:97]
	v_mfma_f32_16x16x32_bf16 v[90:93], v[152:155], v[216:219], v[90:93]
	v_mfma_f32_16x16x32_bf16 v[78:81], v[140:143], v[224:227], v[78:81]
	v_mfma_f32_16x16x32_bf16 v[74:77], v[152:155], v[224:227], v[74:77]
	v_mfma_f32_16x16x32_bf16 v[126:129], v[148:151], v[186:189], v[126:129]
	v_mfma_f32_16x16x32_bf16 v[122:125], v[156:159], v[186:189], v[122:125]
	v_mfma_f32_16x16x32_bf16 v[110:113], v[148:151], v[212:215], v[110:113]
	v_mfma_f32_16x16x32_bf16 v[106:109], v[156:159], v[212:215], v[106:109]
	v_mfma_f32_16x16x32_bf16 v[94:97], v[148:151], v[220:223], v[94:97]
	v_mfma_f32_16x16x32_bf16 v[90:93], v[156:159], v[220:223], v[90:93]
	v_mfma_f32_16x16x32_bf16 v[78:81], v[148:151], v[228:231], v[78:81]
	v_mfma_f32_16x16x32_bf16 v[74:77], v[156:159], v[228:231], v[74:77]
	v_mfma_f32_16x16x32_bf16 v[118:121], v[160:163], v[176:179], v[118:121]
	v_mfma_f32_16x16x32_bf16 v[114:117], v[168:171], v[176:179], v[114:117]
	v_mfma_f32_16x16x32_bf16 v[102:105], v[160:163], v[190:193], v[102:105]
	v_mfma_f32_16x16x32_bf16 v[98:101], v[168:171], v[190:193], v[98:101]
	v_mfma_f32_16x16x32_bf16 v[86:89], v[160:163], v[216:219], v[86:89]
	v_mfma_f32_16x16x32_bf16 v[82:85], v[168:171], v[216:219], v[82:85]
	v_mfma_f32_16x16x32_bf16 v[70:73], v[160:163], v[224:227], v[70:73]
	v_mfma_f32_16x16x32_bf16 v[66:69], v[168:171], v[224:227], v[66:69]
	v_mfma_f32_16x16x32_bf16 v[118:121], v[164:167], v[186:189], v[118:121]
	v_mfma_f32_16x16x32_bf16 v[114:117], v[172:175], v[186:189], v[114:117]
	v_mfma_f32_16x16x32_bf16 v[102:105], v[164:167], v[212:215], v[102:105]
	v_mfma_f32_16x16x32_bf16 v[98:101], v[172:175], v[212:215], v[98:101]
	v_mfma_f32_16x16x32_bf16 v[86:89], v[164:167], v[220:223], v[86:89]
	v_mfma_f32_16x16x32_bf16 v[82:85], v[172:175], v[220:223], v[82:85]
	v_mfma_f32_16x16x32_bf16 v[70:73], v[164:167], v[228:231], v[70:73]
	v_mfma_f32_16x16x32_bf16 v[66:69], v[172:175], v[228:231], v[66:69]
	s_barrier
	s_add_i32 s24, s53, s31
	v_lshl_add_u64 v[180:181], v[180:181], 0, s[16:17]
	s_mov_b32 m0, s24
	ds_read_b128 v[176:179], v147 offset:49152
	ds_read_b128 v[186:189], v147 offset:50176
	ds_read_b128 v[190:193], v147 offset:51200
	ds_read_b128 v[212:215], v147 offset:52224
	ds_read_b128 v[216:219], v147 offset:53248
	ds_read_b128 v[220:223], v147 offset:54272
	ds_read_b128 v[224:227], v147 offset:55296
	ds_read_b128 v[228:231], v147 offset:56320
	global_load_lds_dwordx4 v[180:181], off
	s_add_i32 m0, s24, 0x2000
	s_add_u32 s22, s22, 0x40080
	v_lshl_add_u64 v[180:181], v[194:195], 0, s[16:17]
	s_addc_u32 s23, s23, 0
	s_add_i32 s24, s54, s31
	global_load_lds_dwordx4 v[180:181], off
	v_lshl_add_u64 v[180:181], s[22:23], 0, v[0:1]
	s_mov_b32 m0, s24
	s_nop 0
	global_load_lds_dwordx4 v[180:181], off
	v_lshl_add_u64 v[180:181], s[22:23], 0, v[134:135]
	s_add_i32 m0, s24, 0x2000
	s_nop 0
	global_load_lds_dwordx4 v[180:181], off
	v_lshl_add_u64 v[180:181], v[232:233], 0, s[16:17]
	s_mov_b32 m0, s43
	s_nop 0
	global_load_lds_dwordx4 v[180:181], off
	v_lshl_add_u64 v[180:181], v[234:235], 0, s[16:17]
	s_mov_b32 m0, s44
	s_nop 0
	global_load_lds_dwordx4 v[180:181], off
	s_waitcnt vmcnt(8)
	s_waitcnt lgkmcnt(0)
	s_barrier
	s_waitcnt lgkmcnt(0)
	v_mfma_f32_16x16x32_bf16 v[62:65], v[140:143], v[176:179], v[62:65]
	v_mfma_f32_16x16x32_bf16 v[58:61], v[152:155], v[176:179], v[58:61]
	v_mfma_f32_16x16x32_bf16 v[46:49], v[140:143], v[190:193], v[46:49]
	v_mfma_f32_16x16x32_bf16 v[42:45], v[152:155], v[190:193], v[42:45]
	v_mfma_f32_16x16x32_bf16 v[30:33], v[140:143], v[216:219], v[30:33]
	v_mfma_f32_16x16x32_bf16 v[26:29], v[152:155], v[216:219], v[26:29]
	v_mfma_f32_16x16x32_bf16 v[14:17], v[140:143], v[224:227], v[14:17]
	v_mfma_f32_16x16x32_bf16 v[10:13], v[152:155], v[224:227], v[10:13]
	v_mfma_f32_16x16x32_bf16 v[62:65], v[148:151], v[186:189], v[62:65]
	v_mfma_f32_16x16x32_bf16 v[58:61], v[156:159], v[186:189], v[58:61]
	v_mfma_f32_16x16x32_bf16 v[46:49], v[148:151], v[212:215], v[46:49]
	v_mfma_f32_16x16x32_bf16 v[42:45], v[156:159], v[212:215], v[42:45]
	v_mfma_f32_16x16x32_bf16 v[30:33], v[148:151], v[220:223], v[30:33]
	v_mfma_f32_16x16x32_bf16 v[26:29], v[156:159], v[220:223], v[26:29]
	v_mfma_f32_16x16x32_bf16 v[14:17], v[148:151], v[228:231], v[14:17]
	v_mfma_f32_16x16x32_bf16 v[10:13], v[156:159], v[228:231], v[10:13]
	v_mfma_f32_16x16x32_bf16 v[54:57], v[160:163], v[176:179], v[54:57]
	v_mfma_f32_16x16x32_bf16 v[50:53], v[168:171], v[176:179], v[50:53]
	v_mfma_f32_16x16x32_bf16 v[38:41], v[160:163], v[190:193], v[38:41]
	v_mfma_f32_16x16x32_bf16 v[34:37], v[168:171], v[190:193], v[34:37]
	v_mfma_f32_16x16x32_bf16 v[22:25], v[160:163], v[216:219], v[22:25]
	v_mfma_f32_16x16x32_bf16 v[18:21], v[168:171], v[216:219], v[18:21]
	v_mfma_f32_16x16x32_bf16 v[6:9], v[160:163], v[224:227], v[6:9]
	v_mfma_f32_16x16x32_bf16 v[2:5], v[168:171], v[224:227], v[2:5]
	v_mfma_f32_16x16x32_bf16 v[54:57], v[164:167], v[186:189], v[54:57]
	v_mfma_f32_16x16x32_bf16 v[50:53], v[172:175], v[186:189], v[50:53]
	v_mfma_f32_16x16x32_bf16 v[38:41], v[164:167], v[212:215], v[38:41]
	v_mfma_f32_16x16x32_bf16 v[34:37], v[172:175], v[212:215], v[34:37]
	v_mfma_f32_16x16x32_bf16 v[22:25], v[164:167], v[220:223], v[22:25]
	v_mfma_f32_16x16x32_bf16 v[18:21], v[172:175], v[220:223], v[18:21]
	v_mfma_f32_16x16x32_bf16 v[6:9], v[164:167], v[228:231], v[6:9]
	v_mfma_f32_16x16x32_bf16 v[2:5], v[172:175], v[228:231], v[2:5]
	s_barrier
	s_add_i32 s52, s52, 2
	s_add_u32 s20, s20, 0x100
	s_addc_u32 s21, s21, 0
	s_add_u32 s50, s50, 0x100
	s_addc_u32 s51, s51, 0
	s_cmp_gt_u32 s52, 13
	s_cbranch_scc0 .LBB0_684
	s_and_b64 vcc, exec, s[6:7]
	s_cbranch_vccz .LBB0_687
	s_barrier

.LBB0_762:
	s_add_u32 s26, s24, 0x100
	s_addc_u32 s27, s25, 0
	s_add_i32 s63, 0, 0x10000
	s_cmp_eq_u32 s62, 4
	s_cselect_b32 s31, s21, s27
	s_cselect_b32 s30, s20, s26
	v_add_u32_e32 v138, s63, v159
	s_cselect_b32 s29, s19, s61
	s_cselect_b32 s28, s42, s43
	s_add_i32 s64, 0, 0x14000
	ds_read_b128 v[130:133], v138
	ds_read_b128 v[134:137], v138 offset:1024
	ds_read_b128 v[150:153], v138 offset:2048
	ds_read_b128 v[154:157], v138 offset:3072
	v_add_u32_e32 v138, s64, v159
	ds_read_b128 v[162:165], v138
	ds_read_b128 v[166:169], v138 offset:1024
	ds_read_b128 v[170:173], v138 offset:2048
	ds_read_b128 v[174:177], v138 offset:3072
	v_lshl_add_u64 v[138:139], s[24:25], 0, v[146:147]
	s_add_i32 m0, s5, 0xc000
	ds_read_b128 v[178:181], v161
	ds_read_b128 v[186:189], v161 offset:1024
	ds_read_b128 v[190:193], v161 offset:2048
	ds_read_b128 v[212:215], v161 offset:3072
	ds_read_b128 v[216:219], v161 offset:4096
	ds_read_b128 v[220:223], v161 offset:5120
	ds_read_b128 v[224:227], v161 offset:6144
	ds_read_b128 v[228:231], v161 offset:7168
	global_load_lds_dwordx4 v[138:139], off
	v_lshl_add_u64 v[138:139], s[24:25], 0, v[148:149]
	s_add_i32 m0, s5, 0xe000
	s_nop 0
	global_load_lds_dwordx4 v[138:139], off
	s_waitcnt vmcnt(8)
	s_waitcnt lgkmcnt(0)
	s_barrier
	s_waitcnt lgkmcnt(0)
	v_mfma_f32_16x16x32_bf16 v[126:129], v[130:133], v[178:181], v[126:129]
	v_mfma_f32_16x16x32_bf16 v[122:125], v[150:153], v[178:181], v[122:125]
	v_mfma_f32_16x16x32_bf16 v[110:113], v[130:133], v[190:193], v[110:113]
	v_mfma_f32_16x16x32_bf16 v[106:109], v[150:153], v[190:193], v[106:109]
	v_mfma_f32_16x16x32_bf16 v[94:97], v[130:133], v[216:219], v[94:97]
	v_mfma_f32_16x16x32_bf16 v[90:93], v[150:153], v[216:219], v[90:93]
	v_mfma_f32_16x16x32_bf16 v[78:81], v[130:133], v[224:227], v[78:81]
	v_mfma_f32_16x16x32_bf16 v[74:77], v[150:153], v[224:227], v[74:77]
	v_mfma_f32_16x16x32_bf16 v[126:129], v[134:137], v[186:189], v[126:129]
	v_mfma_f32_16x16x32_bf16 v[122:125], v[154:157], v[186:189], v[122:125]
	v_mfma_f32_16x16x32_bf16 v[110:113], v[134:137], v[212:215], v[110:113]
	v_mfma_f32_16x16x32_bf16 v[106:109], v[154:157], v[212:215], v[106:109]
	v_mfma_f32_16x16x32_bf16 v[94:97], v[134:137], v[220:223], v[94:97]
	v_mfma_f32_16x16x32_bf16 v[90:93], v[154:157], v[220:223], v[90:93]
	v_mfma_f32_16x16x32_bf16 v[78:81], v[134:137], v[228:231], v[78:81]
	v_mfma_f32_16x16x32_bf16 v[74:77], v[154:157], v[228:231], v[74:77]
	v_mfma_f32_16x16x32_bf16 v[118:121], v[162:165], v[178:181], v[118:121]
	v_mfma_f32_16x16x32_bf16 v[114:117], v[170:173], v[178:181], v[114:117]
	v_mfma_f32_16x16x32_bf16 v[102:105], v[162:165], v[190:193], v[102:105]
	v_mfma_f32_16x16x32_bf16 v[98:101], v[170:173], v[190:193], v[98:101]
	v_mfma_f32_16x16x32_bf16 v[86:89], v[162:165], v[216:219], v[86:89]
	v_mfma_f32_16x16x32_bf16 v[82:85], v[170:173], v[216:219], v[82:85]
	v_mfma_f32_16x16x32_bf16 v[70:73], v[162:165], v[224:227], v[70:73]
	v_mfma_f32_16x16x32_bf16 v[66:69], v[170:173], v[224:227], v[66:69]
	v_mfma_f32_16x16x32_bf16 v[118:121], v[166:169], v[186:189], v[118:121]
	v_mfma_f32_16x16x32_bf16 v[114:117], v[174:177], v[186:189], v[114:117]
	v_mfma_f32_16x16x32_bf16 v[102:105], v[166:169], v[212:215], v[102:105]
	v_mfma_f32_16x16x32_bf16 v[98:101], v[174:177], v[212:215], v[98:101]
	v_mfma_f32_16x16x32_bf16 v[86:89], v[166:169], v[220:223], v[86:89]
	v_mfma_f32_16x16x32_bf16 v[82:85], v[174:177], v[220:223], v[82:85]
	v_mfma_f32_16x16x32_bf16 v[70:73], v[166:169], v[228:231], v[70:73]
	v_mfma_f32_16x16x32_bf16 v[66:69], v[174:177], v[228:231], v[66:69]
	s_barrier
	s_add_i32 s24, s63, s51
	v_lshl_add_u64 v[138:139], s[28:29], 0, v[0:1]
	s_mov_b32 m0, s24
	ds_read_b128 v[178:181], v161 offset:16384
	ds_read_b128 v[186:189], v161 offset:17408
	ds_read_b128 v[190:193], v161 offset:18432
	ds_read_b128 v[212:215], v161 offset:19456
	ds_read_b128 v[216:219], v161 offset:20480
	ds_read_b128 v[220:223], v161 offset:21504
	ds_read_b128 v[224:227], v161 offset:22528
	ds_read_b128 v[228:231], v161 offset:23552
	global_load_lds_dwordx4 v[138:139], off
	s_add_i32 m0, s24, 0x2000
	s_add_u32 s24, s28, 0x20000
	v_lshl_add_u64 v[194:195], s[28:29], 0, v[144:145]
	s_addc_u32 s25, s29, 0
	s_add_i32 s63, s64, s51
	global_load_lds_dwordx4 v[194:195], off
	v_lshl_add_u64 v[232:233], s[24:25], 0, v[0:1]
	s_mov_b32 m0, s63
	v_lshl_add_u64 v[234:235], s[30:31], 0, v[142:143]
	global_load_lds_dwordx4 v[232:233], off
	v_lshl_add_u64 v[232:233], s[24:25], 0, v[144:145]
	s_add_i32 m0, s63, 0x2000
	s_nop 0
	global_load_lds_dwordx4 v[232:233], off
	v_lshl_add_u64 v[232:233], s[30:31], 0, v[140:141]
	s_mov_b32 m0, s5
	s_nop 0
	global_load_lds_dwordx4 v[232:233], off
	s_mov_b32 m0, s52
	s_nop 0
	global_load_lds_dwordx4 v[234:235], off
	s_waitcnt vmcnt(8)
	s_waitcnt lgkmcnt(0)
	s_barrier
	s_waitcnt lgkmcnt(0)
	v_mfma_f32_16x16x32_bf16 v[62:65], v[130:133], v[178:181], v[62:65]
	v_mfma_f32_16x16x32_bf16 v[58:61], v[150:153], v[178:181], v[58:61]
	v_mfma_f32_16x16x32_bf16 v[46:49], v[130:133], v[190:193], v[46:49]
	v_mfma_f32_16x16x32_bf16 v[42:45], v[150:153], v[190:193], v[42:45]
	v_mfma_f32_16x16x32_bf16 v[30:33], v[130:133], v[216:219], v[30:33]
	v_mfma_f32_16x16x32_bf16 v[26:29], v[150:153], v[216:219], v[26:29]
	v_mfma_f32_16x16x32_bf16 v[14:17], v[130:133], v[224:227], v[14:17]
	v_mfma_f32_16x16x32_bf16 v[10:13], v[150:153], v[224:227], v[10:13]
	v_mfma_f32_16x16x32_bf16 v[62:65], v[134:137], v[186:189], v[62:65]
	v_mfma_f32_16x16x32_bf16 v[58:61], v[154:157], v[186:189], v[58:61]
	v_mfma_f32_16x16x32_bf16 v[46:49], v[134:137], v[212:215], v[46:49]
	v_mfma_f32_16x16x32_bf16 v[42:45], v[154:157], v[212:215], v[42:45]
	v_mfma_f32_16x16x32_bf16 v[30:33], v[134:137], v[220:223], v[30:33]
	v_mfma_f32_16x16x32_bf16 v[26:29], v[154:157], v[220:223], v[26:29]
	v_mfma_f32_16x16x32_bf16 v[14:17], v[134:137], v[228:231], v[14:17]
	v_mfma_f32_16x16x32_bf16 v[10:13], v[154:157], v[228:231], v[10:13]
	v_mfma_f32_16x16x32_bf16 v[54:57], v[162:165], v[178:181], v[54:57]
	v_mfma_f32_16x16x32_bf16 v[50:53], v[170:173], v[178:181], v[50:53]
	v_mfma_f32_16x16x32_bf16 v[38:41], v[162:165], v[190:193], v[38:41]
	v_mfma_f32_16x16x32_bf16 v[34:37], v[170:173], v[190:193], v[34:37]
	v_mfma_f32_16x16x32_bf16 v[22:25], v[162:165], v[216:219], v[22:25]
	v_mfma_f32_16x16x32_bf16 v[18:21], v[170:173], v[216:219], v[18:21]
	v_mfma_f32_16x16x32_bf16 v[6:9], v[162:165], v[224:227], v[6:9]
	v_mfma_f32_16x16x32_bf16 v[2:5], v[170:173], v[224:227], v[2:5]
	v_mfma_f32_16x16x32_bf16 v[54:57], v[166:169], v[186:189], v[54:57]
	v_mfma_f32_16x16x32_bf16 v[50:53], v[174:177], v[186:189], v[50:53]
	v_mfma_f32_16x16x32_bf16 v[38:41], v[166:169], v[212:215], v[38:41]
	v_mfma_f32_16x16x32_bf16 v[34:37], v[174:177], v[212:215], v[34:37]
	v_mfma_f32_16x16x32_bf16 v[22:25], v[166:169], v[220:223], v[22:25]
	v_mfma_f32_16x16x32_bf16 v[18:21], v[174:177], v[220:223], v[18:21]
	v_mfma_f32_16x16x32_bf16 v[6:9], v[166:169], v[228:231], v[6:9]
	v_mfma_f32_16x16x32_bf16 v[2:5], v[174:177], v[228:231], v[2:5]
	s_barrier
	s_add_i32 s63, 0, 0x18000
	s_add_i32 s64, 0, 0x1c000
	v_add_u32_e32 v154, s63, v159
	v_add_u32_e32 v174, s64, v159
	ds_read_b128 v[130:133], v154
	ds_read_b128 v[134:137], v154 offset:1024
	ds_read_b128 v[150:153], v154 offset:2048
	ds_read_b128 v[154:157], v154 offset:3072
	ds_read_b128 v[162:165], v174
	ds_read_b128 v[166:169], v174 offset:1024
	ds_read_b128 v[170:173], v174 offset:2048
	ds_read_b128 v[174:177], v174 offset:3072
	s_add_u32 s24, s30, 0x60000
	s_addc_u32 s25, s31, 0
	s_mov_b32 m0, s53
	v_lshl_add_u64 v[236:237], s[24:25], 0, v[140:141]
	ds_read_b128 v[178:181], v161 offset:32768
	ds_read_b128 v[186:189], v161 offset:33792
	ds_read_b128 v[190:193], v161 offset:34816
	ds_read_b128 v[212:215], v161 offset:35840
	ds_read_b128 v[216:219], v161 offset:36864
	ds_read_b128 v[220:223], v161 offset:37888
	ds_read_b128 v[224:227], v161 offset:38912
	ds_read_b128 v[228:231], v161 offset:39936
	global_load_lds_dwordx4 v[236:237], off
	v_lshl_add_u64 v[236:237], s[24:25], 0, v[142:143]
	s_mov_b32 m0, s54
	s_nop 0
	global_load_lds_dwordx4 v[236:237], off
	s_waitcnt vmcnt(8)
	s_waitcnt lgkmcnt(0)
	s_barrier
	s_waitcnt lgkmcnt(0)
	v_mfma_f32_16x16x32_bf16 v[126:129], v[130:133], v[178:181], v[126:129]
	v_mfma_f32_16x16x32_bf16 v[122:125], v[150:153], v[178:181], v[122:125]
	v_mfma_f32_16x16x32_bf16 v[110:113], v[130:133], v[190:193], v[110:113]
	v_mfma_f32_16x16x32_bf16 v[106:109], v[150:153], v[190:193], v[106:109]
	v_mfma_f32_16x16x32_bf16 v[94:97], v[130:133], v[216:219], v[94:97]
	v_mfma_f32_16x16x32_bf16 v[90:93], v[150:153], v[216:219], v[90:93]
	v_mfma_f32_16x16x32_bf16 v[78:81], v[130:133], v[224:227], v[78:81]
	v_mfma_f32_16x16x32_bf16 v[74:77], v[150:153], v[224:227], v[74:77]
	v_mfma_f32_16x16x32_bf16 v[126:129], v[134:137], v[186:189], v[126:129]
	v_mfma_f32_16x16x32_bf16 v[122:125], v[154:157], v[186:189], v[122:125]
	v_mfma_f32_16x16x32_bf16 v[110:113], v[134:137], v[212:215], v[110:113]
	v_mfma_f32_16x16x32_bf16 v[106:109], v[154:157], v[212:215], v[106:109]
	v_mfma_f32_16x16x32_bf16 v[94:97], v[134:137], v[220:223], v[94:97]
	v_mfma_f32_16x16x32_bf16 v[90:93], v[154:157], v[220:223], v[90:93]
	v_mfma_f32_16x16x32_bf16 v[78:81], v[134:137], v[228:231], v[78:81]
	v_mfma_f32_16x16x32_bf16 v[74:77], v[154:157], v[228:231], v[74:77]
	v_mfma_f32_16x16x32_bf16 v[118:121], v[162:165], v[178:181], v[118:121]
	v_mfma_f32_16x16x32_bf16 v[114:117], v[170:173], v[178:181], v[114:117]
	v_mfma_f32_16x16x32_bf16 v[102:105], v[162:165], v[190:193], v[102:105]
	v_mfma_f32_16x16x32_bf16 v[98:101], v[170:173], v[190:193], v[98:101]
	v_mfma_f32_16x16x32_bf16 v[86:89], v[162:165], v[216:219], v[86:89]
	v_mfma_f32_16x16x32_bf16 v[82:85], v[170:173], v[216:219], v[82:85]
	v_mfma_f32_16x16x32_bf16 v[70:73], v[162:165], v[224:227], v[70:73]
	v_mfma_f32_16x16x32_bf16 v[66:69], v[170:173], v[224:227], v[66:69]
	v_mfma_f32_16x16x32_bf16 v[118:121], v[166:169], v[186:189], v[118:121]
	v_mfma_f32_16x16x32_bf16 v[114:117], v[174:177], v[186:189], v[114:117]
	v_mfma_f32_16x16x32_bf16 v[102:105], v[166:169], v[212:215], v[102:105]
	v_mfma_f32_16x16x32_bf16 v[98:101], v[174:177], v[212:215], v[98:101]
	v_mfma_f32_16x16x32_bf16 v[86:89], v[166:169], v[220:223], v[86:89]
	v_mfma_f32_16x16x32_bf16 v[82:85], v[174:177], v[220:223], v[82:85]
	v_mfma_f32_16x16x32_bf16 v[70:73], v[166:169], v[228:231], v[70:73]
	v_mfma_f32_16x16x32_bf16 v[66:69], v[174:177], v[228:231], v[66:69]
	s_barrier
	s_add_i32 s24, s63, s51
	v_lshl_add_u64 v[138:139], v[138:139], 0, s[16:17]
	s_mov_b32 m0, s24
	ds_read_b128 v[178:181], v161 offset:49152
	ds_read_b128 v[186:189], v161 offset:50176
	ds_read_b128 v[190:193], v161 offset:51200
	ds_read_b128 v[212:215], v161 offset:52224
	ds_read_b128 v[216:219], v161 offset:53248
	ds_read_b128 v[220:223], v161 offset:54272
	ds_read_b128 v[224:227], v161 offset:55296
	ds_read_b128 v[228:231], v161 offset:56320
	global_load_lds_dwordx4 v[138:139], off
	s_add_i32 m0, s24, 0x2000
	s_add_u32 s24, s28, 0x20080
	v_lshl_add_u64 v[138:139], v[194:195], 0, s[16:17]
	s_addc_u32 s25, s29, 0
	s_add_i32 s28, s64, s51
	global_load_lds_dwordx4 v[138:139], off
	v_lshl_add_u64 v[138:139], s[24:25], 0, v[0:1]
	s_mov_b32 m0, s28
	s_nop 0
	global_load_lds_dwordx4 v[138:139], off
	v_lshl_add_u64 v[138:139], s[24:25], 0, v[144:145]
	s_add_i32 m0, s28, 0x2000
	s_nop 0
	global_load_lds_dwordx4 v[138:139], off
	v_lshl_add_u64 v[138:139], v[232:233], 0, s[16:17]
	s_mov_b32 m0, s56
	s_nop 0
	global_load_lds_dwordx4 v[138:139], off
	v_lshl_add_u64 v[138:139], v[234:235], 0, s[16:17]
	s_mov_b32 m0, s57
	s_nop 0
	global_load_lds_dwordx4 v[138:139], off
	s_waitcnt vmcnt(8)
	s_waitcnt lgkmcnt(0)
	s_barrier
	s_waitcnt lgkmcnt(0)
	v_mfma_f32_16x16x32_bf16 v[62:65], v[130:133], v[178:181], v[62:65]
	v_mfma_f32_16x16x32_bf16 v[58:61], v[150:153], v[178:181], v[58:61]
	v_mfma_f32_16x16x32_bf16 v[46:49], v[130:133], v[190:193], v[46:49]
	v_mfma_f32_16x16x32_bf16 v[42:45], v[150:153], v[190:193], v[42:45]
	v_mfma_f32_16x16x32_bf16 v[30:33], v[130:133], v[216:219], v[30:33]
	v_mfma_f32_16x16x32_bf16 v[26:29], v[150:153], v[216:219], v[26:29]
	v_mfma_f32_16x16x32_bf16 v[14:17], v[130:133], v[224:227], v[14:17]
	v_mfma_f32_16x16x32_bf16 v[10:13], v[150:153], v[224:227], v[10:13]
	v_mfma_f32_16x16x32_bf16 v[62:65], v[134:137], v[186:189], v[62:65]
	v_mfma_f32_16x16x32_bf16 v[58:61], v[154:157], v[186:189], v[58:61]
	v_mfma_f32_16x16x32_bf16 v[46:49], v[134:137], v[212:215], v[46:49]
	v_mfma_f32_16x16x32_bf16 v[42:45], v[154:157], v[212:215], v[42:45]
	v_mfma_f32_16x16x32_bf16 v[30:33], v[134:137], v[220:223], v[30:33]
	v_mfma_f32_16x16x32_bf16 v[26:29], v[154:157], v[220:223], v[26:29]
	v_mfma_f32_16x16x32_bf16 v[14:17], v[134:137], v[228:231], v[14:17]
	v_mfma_f32_16x16x32_bf16 v[10:13], v[154:157], v[228:231], v[10:13]
	v_mfma_f32_16x16x32_bf16 v[54:57], v[162:165], v[178:181], v[54:57]
	v_mfma_f32_16x16x32_bf16 v[50:53], v[170:173], v[178:181], v[50:53]
	v_mfma_f32_16x16x32_bf16 v[38:41], v[162:165], v[190:193], v[38:41]
	v_mfma_f32_16x16x32_bf16 v[34:37], v[170:173], v[190:193], v[34:37]
	v_mfma_f32_16x16x32_bf16 v[22:25], v[162:165], v[216:219], v[22:25]
	v_mfma_f32_16x16x32_bf16 v[18:21], v[170:173], v[216:219], v[18:21]
	v_mfma_f32_16x16x32_bf16 v[6:9], v[162:165], v[224:227], v[6:9]
	v_mfma_f32_16x16x32_bf16 v[2:5], v[170:173], v[224:227], v[2:5]
	v_mfma_f32_16x16x32_bf16 v[54:57], v[166:169], v[186:189], v[54:57]
	v_mfma_f32_16x16x32_bf16 v[50:53], v[174:177], v[186:189], v[50:53]
	v_mfma_f32_16x16x32_bf16 v[38:41], v[166:169], v[212:215], v[38:41]
	v_mfma_f32_16x16x32_bf16 v[34:37], v[174:177], v[212:215], v[34:37]
	v_mfma_f32_16x16x32_bf16 v[22:25], v[166:169], v[220:223], v[22:25]
	v_mfma_f32_16x16x32_bf16 v[18:21], v[174:177], v[220:223], v[18:21]
	v_mfma_f32_16x16x32_bf16 v[6:9], v[166:169], v[228:231], v[6:9]
	v_mfma_f32_16x16x32_bf16 v[2:5], v[174:177], v[228:231], v[2:5]
	s_barrier
	s_add_i32 s62, s62, 2
	s_add_u32 s43, s43, 0x100
	s_addc_u32 s61, s61, 0
	s_cmp_gt_u32 s62, 5
	s_mov_b64 s[24:25], s[26:27]
	s_cbranch_scc0 .LBB0_762
	s_and_b64 vcc, exec, s[14:15]
	s_cbranch_vccz .LBB0_765
	s_barrier

.LBB0_883:
	s_add_i32 s23, s21, 2
	s_add_u32 s26, s24, 0xfffc0080
	s_addc_u32 s27, s25, -1
	s_add_i32 s69, 0, 0x10000
	s_cmp_eq_u32 s59, s21
	s_cselect_b32 s29, s15, s27
	s_cselect_b32 s28, s14, s26
	s_cselect_b32 s27, s19, s13
	s_cselect_b32 s26, s18, s11
	s_add_i32 s21, 0, 0x14000
	v_add_u32_e32 v148, s69, v164
	v_add_u32_e32 v160, s21, v164
	ds_read_b128 v[130:133], v148
	ds_read_b128 v[140:143], v148 offset:1024
	ds_read_b128 v[144:147], v148 offset:2048
	ds_read_b128 v[148:151], v148 offset:3072
	ds_read_b128 v[152:155], v160
	ds_read_b128 v[156:159], v160 offset:1024
	ds_read_b128 v[166:169], v160 offset:2048
	ds_read_b128 v[170:173], v160 offset:3072
	v_lshl_add_u64 v[160:161], s[24:25], 0, v[136:137]
	s_add_i32 m0, s50, 0xc000
	ds_read_b128 v[174:177], v165
	ds_read_b128 v[178:181], v165 offset:1024
	ds_read_b128 v[186:189], v165 offset:2048
	ds_read_b128 v[190:193], v165 offset:3072
	ds_read_b128 v[212:215], v165 offset:4096
	ds_read_b128 v[216:219], v165 offset:5120
	ds_read_b128 v[220:223], v165 offset:6144
	ds_read_b128 v[224:227], v165 offset:7168
	global_load_lds_dwordx4 v[160:161], off
	v_lshl_add_u64 v[160:161], s[24:25], 0, v[138:139]
	s_add_i32 m0, s50, 0xe000
	s_nop 0
	global_load_lds_dwordx4 v[160:161], off
	s_waitcnt vmcnt(8)
	s_waitcnt lgkmcnt(0)
	s_barrier
	s_waitcnt lgkmcnt(0)
	v_mfma_f32_16x16x32_bf16 v[126:129], v[130:133], v[174:177], v[126:129]
	v_mfma_f32_16x16x32_bf16 v[102:105], v[144:147], v[174:177], v[102:105]
	v_mfma_f32_16x16x32_bf16 v[122:125], v[130:133], v[186:189], v[122:125]
	v_mfma_f32_16x16x32_bf16 v[94:97], v[144:147], v[186:189], v[94:97]
	v_mfma_f32_16x16x32_bf16 v[118:121], v[130:133], v[212:215], v[118:121]
	v_mfma_f32_16x16x32_bf16 v[90:93], v[144:147], v[212:215], v[90:93]
	v_mfma_f32_16x16x32_bf16 v[114:117], v[130:133], v[220:223], v[114:117]
	v_mfma_f32_16x16x32_bf16 v[86:89], v[144:147], v[220:223], v[86:89]
	v_mfma_f32_16x16x32_bf16 v[126:129], v[140:143], v[178:181], v[126:129]
	v_mfma_f32_16x16x32_bf16 v[102:105], v[148:151], v[178:181], v[102:105]
	v_mfma_f32_16x16x32_bf16 v[122:125], v[140:143], v[190:193], v[122:125]
	v_mfma_f32_16x16x32_bf16 v[94:97], v[148:151], v[190:193], v[94:97]
	v_mfma_f32_16x16x32_bf16 v[118:121], v[140:143], v[216:219], v[118:121]
	v_mfma_f32_16x16x32_bf16 v[90:93], v[148:151], v[216:219], v[90:93]
	v_mfma_f32_16x16x32_bf16 v[114:117], v[140:143], v[224:227], v[114:117]
	v_mfma_f32_16x16x32_bf16 v[86:89], v[148:151], v[224:227], v[86:89]
	v_mfma_f32_16x16x32_bf16 v[74:77], v[152:155], v[174:177], v[74:77]
	v_mfma_f32_16x16x32_bf16 v[46:49], v[166:169], v[174:177], v[46:49]
	v_mfma_f32_16x16x32_bf16 v[66:69], v[152:155], v[186:189], v[66:69]
	v_mfma_f32_16x16x32_bf16 v[38:41], v[166:169], v[186:189], v[38:41]
	v_mfma_f32_16x16x32_bf16 v[58:61], v[152:155], v[212:215], v[58:61]
	v_mfma_f32_16x16x32_bf16 v[30:33], v[166:169], v[212:215], v[30:33]
	v_mfma_f32_16x16x32_bf16 v[50:53], v[152:155], v[220:223], v[50:53]
	v_mfma_f32_16x16x32_bf16 v[22:25], v[166:169], v[220:223], v[22:25]
	v_mfma_f32_16x16x32_bf16 v[74:77], v[156:159], v[178:181], v[74:77]
	v_mfma_f32_16x16x32_bf16 v[46:49], v[170:173], v[178:181], v[46:49]
	v_mfma_f32_16x16x32_bf16 v[66:69], v[156:159], v[190:193], v[66:69]
	v_mfma_f32_16x16x32_bf16 v[38:41], v[170:173], v[190:193], v[38:41]
	v_mfma_f32_16x16x32_bf16 v[58:61], v[156:159], v[216:219], v[58:61]
	v_mfma_f32_16x16x32_bf16 v[30:33], v[170:173], v[216:219], v[30:33]
	v_mfma_f32_16x16x32_bf16 v[50:53], v[156:159], v[224:227], v[50:53]
	v_mfma_f32_16x16x32_bf16 v[22:25], v[170:173], v[224:227], v[22:25]
	s_barrier
	s_add_i32 s69, s69, s37
	v_lshl_add_u64 v[160:161], s[26:27], 0, v[0:1]
	s_mov_b32 m0, s69
	ds_read_b128 v[174:177], v165 offset:16384
	ds_read_b128 v[178:181], v165 offset:17408
	ds_read_b128 v[186:189], v165 offset:18432
	ds_read_b128 v[190:193], v165 offset:19456
	ds_read_b128 v[212:215], v165 offset:20480
	ds_read_b128 v[216:219], v165 offset:21504
	ds_read_b128 v[220:223], v165 offset:22528
	ds_read_b128 v[224:227], v165 offset:23552
	global_load_lds_dwordx4 v[160:161], off
	s_add_i32 m0, s69, 0x2000
	s_add_u32 s70, s26, 0x40000
	v_lshl_add_u64 v[194:195], s[26:27], 0, v[134:135]
	s_addc_u32 s71, s27, 0
	s_add_i32 s21, s21, s37
	global_load_lds_dwordx4 v[194:195], off
	v_lshl_add_u64 v[228:229], s[70:71], 0, v[0:1]
	s_mov_b32 m0, s21
	v_lshl_add_u64 v[230:231], s[28:29], 0, v[134:135]
	global_load_lds_dwordx4 v[228:229], off
	v_lshl_add_u64 v[228:229], s[70:71], 0, v[134:135]
	s_add_i32 m0, s21, 0x2000
	s_nop 0
	global_load_lds_dwordx4 v[228:229], off
	v_lshl_add_u64 v[228:229], s[28:29], 0, v[0:1]
	s_mov_b32 m0, s50
	s_nop 0
	global_load_lds_dwordx4 v[228:229], off
	s_mov_b32 m0, s51
	s_nop 0
	global_load_lds_dwordx4 v[230:231], off
	s_waitcnt vmcnt(8)
	s_waitcnt lgkmcnt(0)
	s_barrier
	s_waitcnt lgkmcnt(0)
	v_mfma_f32_16x16x32_bf16 v[110:113], v[130:133], v[174:177], v[110:113]
	v_mfma_f32_16x16x32_bf16 v[78:81], v[144:147], v[174:177], v[78:81]
	v_mfma_f32_16x16x32_bf16 v[106:109], v[130:133], v[186:189], v[106:109]
	v_mfma_f32_16x16x32_bf16 v[70:73], v[144:147], v[186:189], v[70:73]
	v_mfma_f32_16x16x32_bf16 v[98:101], v[130:133], v[212:215], v[98:101]
	v_mfma_f32_16x16x32_bf16 v[62:65], v[144:147], v[212:215], v[62:65]
	v_mfma_f32_16x16x32_bf16 v[82:85], v[130:133], v[220:223], v[82:85]
	v_mfma_f32_16x16x32_bf16 v[54:57], v[144:147], v[220:223], v[54:57]
	v_mfma_f32_16x16x32_bf16 v[110:113], v[140:143], v[178:181], v[110:113]
	v_mfma_f32_16x16x32_bf16 v[78:81], v[148:151], v[178:181], v[78:81]
	v_mfma_f32_16x16x32_bf16 v[106:109], v[140:143], v[190:193], v[106:109]
	v_mfma_f32_16x16x32_bf16 v[70:73], v[148:151], v[190:193], v[70:73]
	v_mfma_f32_16x16x32_bf16 v[98:101], v[140:143], v[216:219], v[98:101]
	v_mfma_f32_16x16x32_bf16 v[62:65], v[148:151], v[216:219], v[62:65]
	v_mfma_f32_16x16x32_bf16 v[82:85], v[140:143], v[224:227], v[82:85]
	v_mfma_f32_16x16x32_bf16 v[54:57], v[148:151], v[224:227], v[54:57]
	v_mfma_f32_16x16x32_bf16 v[42:45], v[152:155], v[174:177], v[42:45]
	v_mfma_f32_16x16x32_bf16 v[14:17], v[166:169], v[174:177], v[14:17]
	v_mfma_f32_16x16x32_bf16 v[34:37], v[152:155], v[186:189], v[34:37]
	v_mfma_f32_16x16x32_bf16 v[10:13], v[166:169], v[186:189], v[10:13]
	v_mfma_f32_16x16x32_bf16 v[26:29], v[152:155], v[212:215], v[26:29]
	v_mfma_f32_16x16x32_bf16 v[6:9], v[166:169], v[212:215], v[6:9]
	v_mfma_f32_16x16x32_bf16 v[18:21], v[152:155], v[220:223], v[18:21]
	v_mfma_f32_16x16x32_bf16 v[2:5], v[166:169], v[220:223], v[2:5]
	v_mfma_f32_16x16x32_bf16 v[42:45], v[156:159], v[178:181], v[42:45]
	v_mfma_f32_16x16x32_bf16 v[14:17], v[170:173], v[178:181], v[14:17]
	v_mfma_f32_16x16x32_bf16 v[34:37], v[156:159], v[190:193], v[34:37]
	v_mfma_f32_16x16x32_bf16 v[10:13], v[170:173], v[190:193], v[10:13]
	v_mfma_f32_16x16x32_bf16 v[26:29], v[156:159], v[216:219], v[26:29]
	v_mfma_f32_16x16x32_bf16 v[6:9], v[170:173], v[216:219], v[6:9]
	v_mfma_f32_16x16x32_bf16 v[18:21], v[156:159], v[224:227], v[18:21]
	v_mfma_f32_16x16x32_bf16 v[2:5], v[170:173], v[224:227], v[2:5]
	s_barrier
	s_add_i32 s21, 0, 0x18000
	s_add_i32 s69, 0, 0x1c000
	v_add_u32_e32 v148, s21, v164
	v_add_u32_e32 v170, s69, v164
	ds_read_b128 v[130:133], v148
	ds_read_b128 v[140:143], v148 offset:1024
	ds_read_b128 v[144:147], v148 offset:2048
	ds_read_b128 v[148:151], v148 offset:3072
	ds_read_b128 v[152:155], v170
	ds_read_b128 v[156:159], v170 offset:1024
	ds_read_b128 v[166:169], v170 offset:2048
	ds_read_b128 v[170:173], v170 offset:3072
	s_add_u32 s28, s28, 0x40000
	s_addc_u32 s29, s29, 0
	s_mov_b32 m0, s52
	v_lshl_add_u64 v[232:233], s[28:29], 0, v[0:1]
	ds_read_b128 v[174:177], v165 offset:32768
	ds_read_b128 v[178:181], v165 offset:33792
	ds_read_b128 v[186:189], v165 offset:34816
	ds_read_b128 v[190:193], v165 offset:35840
	ds_read_b128 v[212:215], v165 offset:36864
	ds_read_b128 v[216:219], v165 offset:37888
	ds_read_b128 v[220:223], v165 offset:38912
	ds_read_b128 v[224:227], v165 offset:39936
	global_load_lds_dwordx4 v[232:233], off
	v_lshl_add_u64 v[232:233], s[28:29], 0, v[134:135]
	s_mov_b32 m0, s53
	s_nop 0
	global_load_lds_dwordx4 v[232:233], off
	s_waitcnt vmcnt(8)
	s_waitcnt lgkmcnt(0)
	s_barrier
	s_waitcnt lgkmcnt(0)
	v_mfma_f32_16x16x32_bf16 v[126:129], v[130:133], v[174:177], v[126:129]
	v_mfma_f32_16x16x32_bf16 v[102:105], v[144:147], v[174:177], v[102:105]
	v_mfma_f32_16x16x32_bf16 v[122:125], v[130:133], v[186:189], v[122:125]
	v_mfma_f32_16x16x32_bf16 v[94:97], v[144:147], v[186:189], v[94:97]
	v_mfma_f32_16x16x32_bf16 v[118:121], v[130:133], v[212:215], v[118:121]
	v_mfma_f32_16x16x32_bf16 v[90:93], v[144:147], v[212:215], v[90:93]
	v_mfma_f32_16x16x32_bf16 v[114:117], v[130:133], v[220:223], v[114:117]
	v_mfma_f32_16x16x32_bf16 v[86:89], v[144:147], v[220:223], v[86:89]
	v_mfma_f32_16x16x32_bf16 v[126:129], v[140:143], v[178:181], v[126:129]
	v_mfma_f32_16x16x32_bf16 v[102:105], v[148:151], v[178:181], v[102:105]
	v_mfma_f32_16x16x32_bf16 v[122:125], v[140:143], v[190:193], v[122:125]
	v_mfma_f32_16x16x32_bf16 v[94:97], v[148:151], v[190:193], v[94:97]
	v_mfma_f32_16x16x32_bf16 v[118:121], v[140:143], v[216:219], v[118:121]
	v_mfma_f32_16x16x32_bf16 v[90:93], v[148:151], v[216:219], v[90:93]
	v_mfma_f32_16x16x32_bf16 v[114:117], v[140:143], v[224:227], v[114:117]
	v_mfma_f32_16x16x32_bf16 v[86:89], v[148:151], v[224:227], v[86:89]
	v_mfma_f32_16x16x32_bf16 v[74:77], v[152:155], v[174:177], v[74:77]
	v_mfma_f32_16x16x32_bf16 v[46:49], v[166:169], v[174:177], v[46:49]
	v_mfma_f32_16x16x32_bf16 v[66:69], v[152:155], v[186:189], v[66:69]
	v_mfma_f32_16x16x32_bf16 v[38:41], v[166:169], v[186:189], v[38:41]
	v_mfma_f32_16x16x32_bf16 v[58:61], v[152:155], v[212:215], v[58:61]
	v_mfma_f32_16x16x32_bf16 v[30:33], v[166:169], v[212:215], v[30:33]
	v_mfma_f32_16x16x32_bf16 v[50:53], v[152:155], v[220:223], v[50:53]
	v_mfma_f32_16x16x32_bf16 v[22:25], v[166:169], v[220:223], v[22:25]
	v_mfma_f32_16x16x32_bf16 v[74:77], v[156:159], v[178:181], v[74:77]
	v_mfma_f32_16x16x32_bf16 v[46:49], v[170:173], v[178:181], v[46:49]
	v_mfma_f32_16x16x32_bf16 v[66:69], v[156:159], v[190:193], v[66:69]
	v_mfma_f32_16x16x32_bf16 v[38:41], v[170:173], v[190:193], v[38:41]
	v_mfma_f32_16x16x32_bf16 v[58:61], v[156:159], v[216:219], v[58:61]
	v_mfma_f32_16x16x32_bf16 v[30:33], v[170:173], v[216:219], v[30:33]
	v_mfma_f32_16x16x32_bf16 v[50:53], v[156:159], v[224:227], v[50:53]
	v_mfma_f32_16x16x32_bf16 v[22:25], v[170:173], v[224:227], v[22:25]
	s_barrier
	s_add_i32 s21, s21, s37
	v_lshl_add_u64 v[160:161], v[160:161], 0, s[16:17]
	s_mov_b32 m0, s21
	ds_read_b128 v[174:177], v165 offset:49152
	ds_read_b128 v[178:181], v165 offset:50176
	ds_read_b128 v[186:189], v165 offset:51200
	ds_read_b128 v[190:193], v165 offset:52224
	ds_read_b128 v[212:215], v165 offset:53248
	ds_read_b128 v[216:219], v165 offset:54272
	ds_read_b128 v[220:223], v165 offset:55296
	ds_read_b128 v[224:227], v165 offset:56320
	global_load_lds_dwordx4 v[160:161], off
	s_add_i32 m0, s21, 0x2000
	s_add_u32 s26, s26, 0x40080
	v_lshl_add_u64 v[160:161], v[194:195], 0, s[16:17]
	s_addc_u32 s27, s27, 0
	s_add_i32 s21, s69, s37
	global_load_lds_dwordx4 v[160:161], off
	v_lshl_add_u64 v[160:161], s[26:27], 0, v[0:1]
	s_mov_b32 m0, s21
	s_nop 0
	global_load_lds_dwordx4 v[160:161], off
	v_lshl_add_u64 v[160:161], s[26:27], 0, v[134:135]
	s_add_i32 m0, s21, 0x2000
	s_nop 0
	global_load_lds_dwordx4 v[160:161], off
	v_lshl_add_u64 v[160:161], v[228:229], 0, s[16:17]
	s_mov_b32 m0, s57
	s_nop 0
	global_load_lds_dwordx4 v[160:161], off
	v_lshl_add_u64 v[160:161], v[230:231], 0, s[16:17]
	s_mov_b32 m0, s58
	s_nop 0
	global_load_lds_dwordx4 v[160:161], off
	s_waitcnt vmcnt(8)
	s_waitcnt lgkmcnt(0)
	s_barrier
	s_waitcnt lgkmcnt(0)
	v_mfma_f32_16x16x32_bf16 v[110:113], v[130:133], v[174:177], v[110:113]
	v_mfma_f32_16x16x32_bf16 v[78:81], v[144:147], v[174:177], v[78:81]
	v_mfma_f32_16x16x32_bf16 v[106:109], v[130:133], v[186:189], v[106:109]
	v_mfma_f32_16x16x32_bf16 v[70:73], v[144:147], v[186:189], v[70:73]
	v_mfma_f32_16x16x32_bf16 v[98:101], v[130:133], v[212:215], v[98:101]
	v_mfma_f32_16x16x32_bf16 v[62:65], v[144:147], v[212:215], v[62:65]
	v_mfma_f32_16x16x32_bf16 v[82:85], v[130:133], v[220:223], v[82:85]
	v_mfma_f32_16x16x32_bf16 v[54:57], v[144:147], v[220:223], v[54:57]
	v_mfma_f32_16x16x32_bf16 v[110:113], v[140:143], v[178:181], v[110:113]
	v_mfma_f32_16x16x32_bf16 v[78:81], v[148:151], v[178:181], v[78:81]
	v_mfma_f32_16x16x32_bf16 v[106:109], v[140:143], v[190:193], v[106:109]
	v_mfma_f32_16x16x32_bf16 v[70:73], v[148:151], v[190:193], v[70:73]
	v_mfma_f32_16x16x32_bf16 v[98:101], v[140:143], v[216:219], v[98:101]
	v_mfma_f32_16x16x32_bf16 v[62:65], v[148:151], v[216:219], v[62:65]
	v_mfma_f32_16x16x32_bf16 v[82:85], v[140:143], v[224:227], v[82:85]
	v_mfma_f32_16x16x32_bf16 v[54:57], v[148:151], v[224:227], v[54:57]
	v_mfma_f32_16x16x32_bf16 v[42:45], v[152:155], v[174:177], v[42:45]
	v_mfma_f32_16x16x32_bf16 v[14:17], v[166:169], v[174:177], v[14:17]
	v_mfma_f32_16x16x32_bf16 v[34:37], v[152:155], v[186:189], v[34:37]
	v_mfma_f32_16x16x32_bf16 v[10:13], v[166:169], v[186:189], v[10:13]
	v_mfma_f32_16x16x32_bf16 v[26:29], v[152:155], v[212:215], v[26:29]
	v_mfma_f32_16x16x32_bf16 v[6:9], v[166:169], v[212:215], v[6:9]
	v_mfma_f32_16x16x32_bf16 v[18:21], v[152:155], v[220:223], v[18:21]
	v_mfma_f32_16x16x32_bf16 v[2:5], v[166:169], v[220:223], v[2:5]
	v_mfma_f32_16x16x32_bf16 v[42:45], v[156:159], v[178:181], v[42:45]
	v_mfma_f32_16x16x32_bf16 v[14:17], v[170:173], v[178:181], v[14:17]
	v_mfma_f32_16x16x32_bf16 v[34:37], v[156:159], v[190:193], v[34:37]
	v_mfma_f32_16x16x32_bf16 v[10:13], v[170:173], v[190:193], v[10:13]
	v_mfma_f32_16x16x32_bf16 v[26:29], v[156:159], v[216:219], v[26:29]
	v_mfma_f32_16x16x32_bf16 v[6:9], v[170:173], v[216:219], v[6:9]
	v_mfma_f32_16x16x32_bf16 v[18:21], v[156:159], v[224:227], v[18:21]
	v_mfma_f32_16x16x32_bf16 v[2:5], v[170:173], v[224:227], v[2:5]
	s_barrier
	s_add_u32 s24, s24, 0x100
	s_addc_u32 s25, s25, 0
	s_add_u32 s11, s11, 0x100
	s_addc_u32 s13, s13, 0
	s_cmp_ge_u32 s23, s56
	s_mov_b32 s21, s23
	s_cbranch_scc0 .LBB0_883
	s_and_b64 vcc, exec, s[6:7]
	s_cbranch_vccz .LBB0_886
	s_barrier

.LBB0_1027:
	s_add_u32 s26, s24, 0xfffc0080
	s_addc_u32 s27, s25, -1
	s_add_i32 s63, 0, 0x10000
	s_cmp_eq_u32 s62, 12
	s_cselect_b32 s29, s13, s27
	s_cselect_b32 s28, s15, s26
	s_cselect_b32 s27, s11, s61
	s_cselect_b32 s26, s59, s60
	s_add_i32 s67, 0, 0x14000
	v_add_u32_e32 v156, s63, v145
	v_add_u32_e32 v172, s67, v145
	ds_read_b128 v[140:143], v156
	ds_read_b128 v[148:151], v156 offset:1024
	ds_read_b128 v[152:155], v156 offset:2048
	ds_read_b128 v[156:159], v156 offset:3072
	ds_read_b128 v[160:163], v172
	ds_read_b128 v[164:167], v172 offset:1024
	ds_read_b128 v[168:171], v172 offset:2048
	ds_read_b128 v[172:175], v172 offset:3072
	v_lshl_add_u64 v[180:181], s[24:25], 0, v[136:137]
	s_add_i32 m0, s19, 0xc000
	ds_read_b128 v[176:179], v147
	ds_read_b128 v[186:189], v147 offset:1024
	ds_read_b128 v[190:193], v147 offset:2048
	ds_read_b128 v[212:215], v147 offset:3072
	ds_read_b128 v[216:219], v147 offset:4096
	ds_read_b128 v[220:223], v147 offset:5120
	ds_read_b128 v[224:227], v147 offset:6144
	ds_read_b128 v[228:231], v147 offset:7168
	global_load_lds_dwordx4 v[180:181], off
	v_lshl_add_u64 v[180:181], s[24:25], 0, v[138:139]
	s_add_i32 m0, s19, 0xe000
	s_nop 0
	global_load_lds_dwordx4 v[180:181], off
	s_waitcnt vmcnt(8)
	s_waitcnt lgkmcnt(0)
	s_barrier
	s_waitcnt lgkmcnt(0)
	v_mfma_f32_16x16x32_bf16 v[126:129], v[140:143], v[176:179], v[126:129]
	v_mfma_f32_16x16x32_bf16 v[122:125], v[152:155], v[176:179], v[122:125]
	v_mfma_f32_16x16x32_bf16 v[114:117], v[140:143], v[190:193], v[114:117]
	v_mfma_f32_16x16x32_bf16 v[106:109], v[152:155], v[190:193], v[106:109]
	v_mfma_f32_16x16x32_bf16 v[98:101], v[140:143], v[216:219], v[98:101]
	v_mfma_f32_16x16x32_bf16 v[90:93], v[152:155], v[216:219], v[90:93]
	v_mfma_f32_16x16x32_bf16 v[82:85], v[140:143], v[224:227], v[82:85]
	v_mfma_f32_16x16x32_bf16 v[74:77], v[152:155], v[224:227], v[74:77]
	v_mfma_f32_16x16x32_bf16 v[126:129], v[148:151], v[186:189], v[126:129]
	v_mfma_f32_16x16x32_bf16 v[122:125], v[156:159], v[186:189], v[122:125]
	v_mfma_f32_16x16x32_bf16 v[114:117], v[148:151], v[212:215], v[114:117]
	v_mfma_f32_16x16x32_bf16 v[106:109], v[156:159], v[212:215], v[106:109]
	v_mfma_f32_16x16x32_bf16 v[98:101], v[148:151], v[220:223], v[98:101]
	v_mfma_f32_16x16x32_bf16 v[90:93], v[156:159], v[220:223], v[90:93]
	v_mfma_f32_16x16x32_bf16 v[82:85], v[148:151], v[228:231], v[82:85]
	v_mfma_f32_16x16x32_bf16 v[74:77], v[156:159], v[228:231], v[74:77]
	v_mfma_f32_16x16x32_bf16 v[118:121], v[160:163], v[176:179], v[118:121]
	v_mfma_f32_16x16x32_bf16 v[110:113], v[168:171], v[176:179], v[110:113]
	v_mfma_f32_16x16x32_bf16 v[102:105], v[160:163], v[190:193], v[102:105]
	v_mfma_f32_16x16x32_bf16 v[94:97], v[168:171], v[190:193], v[94:97]
	v_mfma_f32_16x16x32_bf16 v[86:89], v[160:163], v[216:219], v[86:89]
	v_mfma_f32_16x16x32_bf16 v[78:81], v[168:171], v[216:219], v[78:81]
	v_mfma_f32_16x16x32_bf16 v[70:73], v[160:163], v[224:227], v[70:73]
	v_mfma_f32_16x16x32_bf16 v[66:69], v[168:171], v[224:227], v[66:69]
	v_mfma_f32_16x16x32_bf16 v[118:121], v[164:167], v[186:189], v[118:121]
	v_mfma_f32_16x16x32_bf16 v[110:113], v[172:175], v[186:189], v[110:113]
	v_mfma_f32_16x16x32_bf16 v[102:105], v[164:167], v[212:215], v[102:105]
	v_mfma_f32_16x16x32_bf16 v[94:97], v[172:175], v[212:215], v[94:97]
	v_mfma_f32_16x16x32_bf16 v[86:89], v[164:167], v[220:223], v[86:89]
	v_mfma_f32_16x16x32_bf16 v[78:81], v[172:175], v[220:223], v[78:81]
	v_mfma_f32_16x16x32_bf16 v[70:73], v[164:167], v[228:231], v[70:73]
	v_mfma_f32_16x16x32_bf16 v[66:69], v[172:175], v[228:231], v[66:69]
	s_barrier
	s_add_i32 s63, s63, s51
	v_lshl_add_u64 v[180:181], s[26:27], 0, v[0:1]
	s_mov_b32 m0, s63
	ds_read_b128 v[176:179], v147 offset:16384
	ds_read_b128 v[186:189], v147 offset:17408
	ds_read_b128 v[190:193], v147 offset:18432
	ds_read_b128 v[212:215], v147 offset:19456
	ds_read_b128 v[216:219], v147 offset:20480
	ds_read_b128 v[220:223], v147 offset:21504
	ds_read_b128 v[224:227], v147 offset:22528
	ds_read_b128 v[228:231], v147 offset:23552
	global_load_lds_dwordx4 v[180:181], off
	s_add_i32 m0, s63, 0x2000
	s_add_u32 s64, s26, 0x40000
	v_lshl_add_u64 v[194:195], s[26:27], 0, v[134:135]
	s_addc_u32 s65, s27, 0
	s_add_i32 s63, s67, s51
	global_load_lds_dwordx4 v[194:195], off
	v_lshl_add_u64 v[232:233], s[64:65], 0, v[0:1]
	s_mov_b32 m0, s63
	v_lshl_add_u64 v[234:235], s[28:29], 0, v[132:133]
	global_load_lds_dwordx4 v[232:233], off
	v_lshl_add_u64 v[232:233], s[64:65], 0, v[134:135]
	s_add_i32 m0, s63, 0x2000
	s_nop 0
	global_load_lds_dwordx4 v[232:233], off
	v_lshl_add_u64 v[232:233], s[28:29], 0, v[130:131]
	s_mov_b32 m0, s19
	s_nop 0
	global_load_lds_dwordx4 v[232:233], off
	s_mov_b32 m0, s52
	s_nop 0
	global_load_lds_dwordx4 v[234:235], off
	s_waitcnt vmcnt(8)
	s_waitcnt lgkmcnt(0)
	s_barrier
	s_waitcnt lgkmcnt(0)
	v_mfma_f32_16x16x32_bf16 v[62:65], v[140:143], v[176:179], v[62:65]
	v_mfma_f32_16x16x32_bf16 v[58:61], v[152:155], v[176:179], v[58:61]
	v_mfma_f32_16x16x32_bf16 v[50:53], v[140:143], v[190:193], v[50:53]
	v_mfma_f32_16x16x32_bf16 v[42:45], v[152:155], v[190:193], v[42:45]
	v_mfma_f32_16x16x32_bf16 v[34:37], v[140:143], v[216:219], v[34:37]
	v_mfma_f32_16x16x32_bf16 v[26:29], v[152:155], v[216:219], v[26:29]
	v_mfma_f32_16x16x32_bf16 v[18:21], v[140:143], v[224:227], v[18:21]
	v_mfma_f32_16x16x32_bf16 v[10:13], v[152:155], v[224:227], v[10:13]
	v_mfma_f32_16x16x32_bf16 v[62:65], v[148:151], v[186:189], v[62:65]
	v_mfma_f32_16x16x32_bf16 v[58:61], v[156:159], v[186:189], v[58:61]
	v_mfma_f32_16x16x32_bf16 v[50:53], v[148:151], v[212:215], v[50:53]
	v_mfma_f32_16x16x32_bf16 v[42:45], v[156:159], v[212:215], v[42:45]
	v_mfma_f32_16x16x32_bf16 v[34:37], v[148:151], v[220:223], v[34:37]
	v_mfma_f32_16x16x32_bf16 v[26:29], v[156:159], v[220:223], v[26:29]
	v_mfma_f32_16x16x32_bf16 v[18:21], v[148:151], v[228:231], v[18:21]
	v_mfma_f32_16x16x32_bf16 v[10:13], v[156:159], v[228:231], v[10:13]
	v_mfma_f32_16x16x32_bf16 v[54:57], v[160:163], v[176:179], v[54:57]
	v_mfma_f32_16x16x32_bf16 v[46:49], v[168:171], v[176:179], v[46:49]
	v_mfma_f32_16x16x32_bf16 v[38:41], v[160:163], v[190:193], v[38:41]
	v_mfma_f32_16x16x32_bf16 v[30:33], v[168:171], v[190:193], v[30:33]
	v_mfma_f32_16x16x32_bf16 v[22:25], v[160:163], v[216:219], v[22:25]
	v_mfma_f32_16x16x32_bf16 v[14:17], v[168:171], v[216:219], v[14:17]
	v_mfma_f32_16x16x32_bf16 v[6:9], v[160:163], v[224:227], v[6:9]
	v_mfma_f32_16x16x32_bf16 v[2:5], v[168:171], v[224:227], v[2:5]
	v_mfma_f32_16x16x32_bf16 v[54:57], v[164:167], v[186:189], v[54:57]
	v_mfma_f32_16x16x32_bf16 v[46:49], v[172:175], v[186:189], v[46:49]
	v_mfma_f32_16x16x32_bf16 v[38:41], v[164:167], v[212:215], v[38:41]
	v_mfma_f32_16x16x32_bf16 v[30:33], v[172:175], v[212:215], v[30:33]
	v_mfma_f32_16x16x32_bf16 v[22:25], v[164:167], v[220:223], v[22:25]
	v_mfma_f32_16x16x32_bf16 v[14:17], v[172:175], v[220:223], v[14:17]
	v_mfma_f32_16x16x32_bf16 v[6:9], v[164:167], v[228:231], v[6:9]
	v_mfma_f32_16x16x32_bf16 v[2:5], v[172:175], v[228:231], v[2:5]
	s_barrier
	s_add_i32 s63, 0, 0x18000
	s_add_i32 s64, 0, 0x1c000
	v_add_u32_e32 v156, s63, v145
	v_add_u32_e32 v172, s64, v145
	ds_read_b128 v[140:143], v156
	ds_read_b128 v[148:151], v156 offset:1024
	ds_read_b128 v[152:155], v156 offset:2048
	ds_read_b128 v[156:159], v156 offset:3072
	ds_read_b128 v[160:163], v172
	ds_read_b128 v[164:167], v172 offset:1024
	ds_read_b128 v[168:171], v172 offset:2048
	ds_read_b128 v[172:175], v172 offset:3072
	s_add_u32 s28, s28, 0x40000
	s_addc_u32 s29, s29, 0
	s_mov_b32 m0, s53
	v_lshl_add_u64 v[236:237], s[28:29], 0, v[130:131]
	ds_read_b128 v[176:179], v147 offset:32768
	ds_read_b128 v[186:189], v147 offset:33792
	ds_read_b128 v[190:193], v147 offset:34816
	ds_read_b128 v[212:215], v147 offset:35840
	ds_read_b128 v[216:219], v147 offset:36864
	ds_read_b128 v[220:223], v147 offset:37888
	ds_read_b128 v[224:227], v147 offset:38912
	ds_read_b128 v[228:231], v147 offset:39936
	global_load_lds_dwordx4 v[236:237], off
	v_lshl_add_u64 v[236:237], s[28:29], 0, v[132:133]
	s_mov_b32 m0, s54
	s_nop 0
	global_load_lds_dwordx4 v[236:237], off
	s_waitcnt vmcnt(8)
	s_waitcnt lgkmcnt(0)
	s_barrier
	s_waitcnt lgkmcnt(0)
	v_mfma_f32_16x16x32_bf16 v[126:129], v[140:143], v[176:179], v[126:129]
	v_mfma_f32_16x16x32_bf16 v[122:125], v[152:155], v[176:179], v[122:125]
	v_mfma_f32_16x16x32_bf16 v[114:117], v[140:143], v[190:193], v[114:117]
	v_mfma_f32_16x16x32_bf16 v[106:109], v[152:155], v[190:193], v[106:109]
	v_mfma_f32_16x16x32_bf16 v[98:101], v[140:143], v[216:219], v[98:101]
	v_mfma_f32_16x16x32_bf16 v[90:93], v[152:155], v[216:219], v[90:93]
	v_mfma_f32_16x16x32_bf16 v[82:85], v[140:143], v[224:227], v[82:85]
	v_mfma_f32_16x16x32_bf16 v[74:77], v[152:155], v[224:227], v[74:77]
	v_mfma_f32_16x16x32_bf16 v[126:129], v[148:151], v[186:189], v[126:129]
	v_mfma_f32_16x16x32_bf16 v[122:125], v[156:159], v[186:189], v[122:125]
	v_mfma_f32_16x16x32_bf16 v[114:117], v[148:151], v[212:215], v[114:117]
	v_mfma_f32_16x16x32_bf16 v[106:109], v[156:159], v[212:215], v[106:109]
	v_mfma_f32_16x16x32_bf16 v[98:101], v[148:151], v[220:223], v[98:101]
	v_mfma_f32_16x16x32_bf16 v[90:93], v[156:159], v[220:223], v[90:93]
	v_mfma_f32_16x16x32_bf16 v[82:85], v[148:151], v[228:231], v[82:85]
	v_mfma_f32_16x16x32_bf16 v[74:77], v[156:159], v[228:231], v[74:77]
	v_mfma_f32_16x16x32_bf16 v[118:121], v[160:163], v[176:179], v[118:121]
	v_mfma_f32_16x16x32_bf16 v[110:113], v[168:171], v[176:179], v[110:113]
	v_mfma_f32_16x16x32_bf16 v[102:105], v[160:163], v[190:193], v[102:105]
	v_mfma_f32_16x16x32_bf16 v[94:97], v[168:171], v[190:193], v[94:97]
	v_mfma_f32_16x16x32_bf16 v[86:89], v[160:163], v[216:219], v[86:89]
	v_mfma_f32_16x16x32_bf16 v[78:81], v[168:171], v[216:219], v[78:81]
	v_mfma_f32_16x16x32_bf16 v[70:73], v[160:163], v[224:227], v[70:73]
	v_mfma_f32_16x16x32_bf16 v[66:69], v[168:171], v[224:227], v[66:69]
	v_mfma_f32_16x16x32_bf16 v[118:121], v[164:167], v[186:189], v[118:121]
	v_mfma_f32_16x16x32_bf16 v[110:113], v[172:175], v[186:189], v[110:113]
	v_mfma_f32_16x16x32_bf16 v[102:105], v[164:167], v[212:215], v[102:105]
	v_mfma_f32_16x16x32_bf16 v[94:97], v[172:175], v[212:215], v[94:97]
	v_mfma_f32_16x16x32_bf16 v[86:89], v[164:167], v[220:223], v[86:89]
	v_mfma_f32_16x16x32_bf16 v[78:81], v[172:175], v[220:223], v[78:81]
	v_mfma_f32_16x16x32_bf16 v[70:73], v[164:167], v[228:231], v[70:73]
	v_mfma_f32_16x16x32_bf16 v[66:69], v[172:175], v[228:231], v[66:69]
	s_barrier
	s_add_i32 s28, s63, s51
	v_lshl_add_u64 v[180:181], v[180:181], 0, s[16:17]
	s_mov_b32 m0, s28
	ds_read_b128 v[176:179], v147 offset:49152
	ds_read_b128 v[186:189], v147 offset:50176
	ds_read_b128 v[190:193], v147 offset:51200
	ds_read_b128 v[212:215], v147 offset:52224
	ds_read_b128 v[216:219], v147 offset:53248
	ds_read_b128 v[220:223], v147 offset:54272
	ds_read_b128 v[224:227], v147 offset:55296
	ds_read_b128 v[228:231], v147 offset:56320
	global_load_lds_dwordx4 v[180:181], off
	s_add_i32 m0, s28, 0x2000
	s_add_u32 s26, s26, 0x40080
	v_lshl_add_u64 v[180:181], v[194:195], 0, s[16:17]
	s_addc_u32 s27, s27, 0
	s_add_i32 s28, s64, s51
	global_load_lds_dwordx4 v[180:181], off
	v_lshl_add_u64 v[180:181], s[26:27], 0, v[0:1]
	s_mov_b32 m0, s28
	s_nop 0
	global_load_lds_dwordx4 v[180:181], off
	v_lshl_add_u64 v[180:181], s[26:27], 0, v[134:135]
	s_add_i32 m0, s28, 0x2000
	s_nop 0
	global_load_lds_dwordx4 v[180:181], off
	v_lshl_add_u64 v[180:181], v[232:233], 0, s[16:17]
	s_mov_b32 m0, s56
	s_nop 0
	global_load_lds_dwordx4 v[180:181], off
	v_lshl_add_u64 v[180:181], v[234:235], 0, s[16:17]
	s_mov_b32 m0, s57
	s_nop 0
	global_load_lds_dwordx4 v[180:181], off
	s_waitcnt vmcnt(8)
	s_waitcnt lgkmcnt(0)
	s_barrier
	s_waitcnt lgkmcnt(0)
	v_mfma_f32_16x16x32_bf16 v[62:65], v[140:143], v[176:179], v[62:65]
	v_mfma_f32_16x16x32_bf16 v[58:61], v[152:155], v[176:179], v[58:61]
	v_mfma_f32_16x16x32_bf16 v[50:53], v[140:143], v[190:193], v[50:53]
	v_mfma_f32_16x16x32_bf16 v[42:45], v[152:155], v[190:193], v[42:45]
	v_mfma_f32_16x16x32_bf16 v[34:37], v[140:143], v[216:219], v[34:37]
	v_mfma_f32_16x16x32_bf16 v[26:29], v[152:155], v[216:219], v[26:29]
	v_mfma_f32_16x16x32_bf16 v[18:21], v[140:143], v[224:227], v[18:21]
	v_mfma_f32_16x16x32_bf16 v[10:13], v[152:155], v[224:227], v[10:13]
	v_mfma_f32_16x16x32_bf16 v[62:65], v[148:151], v[186:189], v[62:65]
	v_mfma_f32_16x16x32_bf16 v[58:61], v[156:159], v[186:189], v[58:61]
	v_mfma_f32_16x16x32_bf16 v[50:53], v[148:151], v[212:215], v[50:53]
	v_mfma_f32_16x16x32_bf16 v[42:45], v[156:159], v[212:215], v[42:45]
	v_mfma_f32_16x16x32_bf16 v[34:37], v[148:151], v[220:223], v[34:37]
	v_mfma_f32_16x16x32_bf16 v[26:29], v[156:159], v[220:223], v[26:29]
	v_mfma_f32_16x16x32_bf16 v[18:21], v[148:151], v[228:231], v[18:21]
	v_mfma_f32_16x16x32_bf16 v[10:13], v[156:159], v[228:231], v[10:13]
	v_mfma_f32_16x16x32_bf16 v[54:57], v[160:163], v[176:179], v[54:57]
	v_mfma_f32_16x16x32_bf16 v[46:49], v[168:171], v[176:179], v[46:49]
	v_mfma_f32_16x16x32_bf16 v[38:41], v[160:163], v[190:193], v[38:41]
	v_mfma_f32_16x16x32_bf16 v[30:33], v[168:171], v[190:193], v[30:33]
	v_mfma_f32_16x16x32_bf16 v[22:25], v[160:163], v[216:219], v[22:25]
	v_mfma_f32_16x16x32_bf16 v[14:17], v[168:171], v[216:219], v[14:17]
	v_mfma_f32_16x16x32_bf16 v[6:9], v[160:163], v[224:227], v[6:9]
	v_mfma_f32_16x16x32_bf16 v[2:5], v[168:171], v[224:227], v[2:5]
	v_mfma_f32_16x16x32_bf16 v[54:57], v[164:167], v[186:189], v[54:57]
	v_mfma_f32_16x16x32_bf16 v[46:49], v[172:175], v[186:189], v[46:49]
	v_mfma_f32_16x16x32_bf16 v[38:41], v[164:167], v[212:215], v[38:41]
	v_mfma_f32_16x16x32_bf16 v[30:33], v[172:175], v[212:215], v[30:33]
	v_mfma_f32_16x16x32_bf16 v[22:25], v[164:167], v[220:223], v[22:25]
	v_mfma_f32_16x16x32_bf16 v[14:17], v[172:175], v[220:223], v[14:17]
	v_mfma_f32_16x16x32_bf16 v[6:9], v[164:167], v[228:231], v[6:9]
	v_mfma_f32_16x16x32_bf16 v[2:5], v[172:175], v[228:231], v[2:5]
	s_barrier
	s_add_i32 s62, s62, 2
	s_add_u32 s24, s24, 0x100
	s_addc_u32 s25, s25, 0
	s_add_u32 s60, s60, 0x100
	s_addc_u32 s61, s61, 0
	s_cmp_gt_u32 s62, 13
	s_cbranch_scc0 .LBB0_1027
	s_and_b64 vcc, exec, s[8:9]
	s_cbranch_vccz .LBB0_1030
	s_barrier

.LBB0_1215:
	s_add_i32 s65, s20, 2
	s_add_u32 s18, s14, 0x100
	s_addc_u32 s19, s15, 0
	s_add_i32 s67, 0, 0x10000
	s_cmp_eq_u32 s50, s20
	s_cselect_b32 s23, s11, s19
	s_cselect_b32 s22, s10, s18
	s_cselect_b32 s21, s13, s64
	s_cselect_b32 s20, s12, s63
	s_add_i32 s68, 0, 0x14000
	v_add_u32_e32 v152, s67, v168
	v_add_u32_e32 v164, s68, v168
	ds_read_b128 v[130:133], v152
	ds_read_b128 v[144:147], v152 offset:1024
	ds_read_b128 v[148:151], v152 offset:2048
	ds_read_b128 v[152:155], v152 offset:3072
	ds_read_b128 v[156:159], v164
	ds_read_b128 v[160:163], v164 offset:1024
	ds_read_b128 v[170:173], v164 offset:2048
	ds_read_b128 v[174:177], v164 offset:3072
	v_lshl_add_u64 v[164:165], s[14:15], 0, v[140:141]
	s_add_i32 m0, s34, 0xc000
	ds_read_b128 v[178:181], v169
	ds_read_b128 v[186:189], v169 offset:1024
	ds_read_b128 v[190:193], v169 offset:2048
	ds_read_b128 v[212:215], v169 offset:3072
	ds_read_b128 v[216:219], v169 offset:4096
	ds_read_b128 v[220:223], v169 offset:5120
	ds_read_b128 v[224:227], v169 offset:6144
	ds_read_b128 v[228:231], v169 offset:7168
	global_load_lds_dwordx4 v[164:165], off
	v_lshl_add_u64 v[164:165], s[14:15], 0, v[142:143]
	s_add_i32 m0, s34, 0xe000
	s_nop 0
	global_load_lds_dwordx4 v[164:165], off
	s_waitcnt vmcnt(8)
	s_waitcnt lgkmcnt(0)
	s_barrier
	s_waitcnt lgkmcnt(0)
	v_mfma_f32_16x16x32_bf16 v[126:129], v[130:133], v[178:181], v[126:129]
	v_mfma_f32_16x16x32_bf16 v[98:101], v[148:151], v[178:181], v[98:101]
	v_mfma_f32_16x16x32_bf16 v[122:125], v[130:133], v[190:193], v[122:125]
	v_mfma_f32_16x16x32_bf16 v[94:97], v[148:151], v[190:193], v[94:97]
	v_mfma_f32_16x16x32_bf16 v[118:121], v[130:133], v[216:219], v[118:121]
	v_mfma_f32_16x16x32_bf16 v[86:89], v[148:151], v[216:219], v[86:89]
	v_mfma_f32_16x16x32_bf16 v[114:117], v[130:133], v[224:227], v[114:117]
	v_mfma_f32_16x16x32_bf16 v[82:85], v[148:151], v[224:227], v[82:85]
	v_mfma_f32_16x16x32_bf16 v[126:129], v[144:147], v[186:189], v[126:129]
	v_mfma_f32_16x16x32_bf16 v[98:101], v[152:155], v[186:189], v[98:101]
	v_mfma_f32_16x16x32_bf16 v[122:125], v[144:147], v[212:215], v[122:125]
	v_mfma_f32_16x16x32_bf16 v[94:97], v[152:155], v[212:215], v[94:97]
	v_mfma_f32_16x16x32_bf16 v[118:121], v[144:147], v[220:223], v[118:121]
	v_mfma_f32_16x16x32_bf16 v[86:89], v[152:155], v[220:223], v[86:89]
	v_mfma_f32_16x16x32_bf16 v[114:117], v[144:147], v[228:231], v[114:117]
	v_mfma_f32_16x16x32_bf16 v[82:85], v[152:155], v[228:231], v[82:85]
	v_mfma_f32_16x16x32_bf16 v[66:69], v[156:159], v[178:181], v[66:69]
	v_mfma_f32_16x16x32_bf16 v[38:41], v[170:173], v[178:181], v[38:41]
	v_mfma_f32_16x16x32_bf16 v[62:65], v[156:159], v[190:193], v[62:65]
	v_mfma_f32_16x16x32_bf16 v[30:33], v[170:173], v[190:193], v[30:33]
	v_mfma_f32_16x16x32_bf16 v[54:57], v[156:159], v[216:219], v[54:57]
	v_mfma_f32_16x16x32_bf16 v[22:25], v[170:173], v[216:219], v[22:25]
	v_mfma_f32_16x16x32_bf16 v[50:53], v[156:159], v[224:227], v[50:53]
	v_mfma_f32_16x16x32_bf16 v[18:21], v[170:173], v[224:227], v[18:21]
	v_mfma_f32_16x16x32_bf16 v[66:69], v[160:163], v[186:189], v[66:69]
	v_mfma_f32_16x16x32_bf16 v[38:41], v[174:177], v[186:189], v[38:41]
	v_mfma_f32_16x16x32_bf16 v[62:65], v[160:163], v[212:215], v[62:65]
	v_mfma_f32_16x16x32_bf16 v[30:33], v[174:177], v[212:215], v[30:33]
	v_mfma_f32_16x16x32_bf16 v[54:57], v[160:163], v[220:223], v[54:57]
	v_mfma_f32_16x16x32_bf16 v[22:25], v[174:177], v[220:223], v[22:25]
	v_mfma_f32_16x16x32_bf16 v[50:53], v[160:163], v[228:231], v[50:53]
	v_mfma_f32_16x16x32_bf16 v[18:21], v[174:177], v[228:231], v[18:21]
	s_barrier
	s_add_i32 s14, s67, s25
	v_lshl_add_u64 v[164:165], s[20:21], 0, v[0:1]
	s_mov_b32 m0, s14
	ds_read_b128 v[178:181], v169 offset:16384
	ds_read_b128 v[186:189], v169 offset:17408
	ds_read_b128 v[190:193], v169 offset:18432
	ds_read_b128 v[212:215], v169 offset:19456
	ds_read_b128 v[216:219], v169 offset:20480
	ds_read_b128 v[220:223], v169 offset:21504
	ds_read_b128 v[224:227], v169 offset:22528
	ds_read_b128 v[228:231], v169 offset:23552
	global_load_lds_dwordx4 v[164:165], off
	s_add_i32 m0, s14, 0x2000
	s_add_u32 s14, s20, 0xb0000
	v_lshl_add_u64 v[194:195], s[20:21], 0, v[138:139]
	s_addc_u32 s15, s21, 0
	s_add_i32 s67, s68, s25
	global_load_lds_dwordx4 v[194:195], off
	v_lshl_add_u64 v[232:233], s[14:15], 0, v[0:1]
	s_mov_b32 m0, s67
	v_lshl_add_u64 v[234:235], s[22:23], 0, v[136:137]
	global_load_lds_dwordx4 v[232:233], off
	v_lshl_add_u64 v[232:233], s[14:15], 0, v[138:139]
	s_add_i32 m0, s67, 0x2000
	s_nop 0
	global_load_lds_dwordx4 v[232:233], off
	v_lshl_add_u64 v[232:233], s[22:23], 0, v[134:135]
	s_mov_b32 m0, s34
	s_nop 0
	global_load_lds_dwordx4 v[232:233], off
	s_mov_b32 m0, s36
	s_nop 0
	global_load_lds_dwordx4 v[234:235], off
	s_waitcnt vmcnt(8)
	s_waitcnt lgkmcnt(0)
	s_barrier
	s_waitcnt lgkmcnt(0)
	v_mfma_f32_16x16x32_bf16 v[110:113], v[130:133], v[178:181], v[110:113]
	v_mfma_f32_16x16x32_bf16 v[78:81], v[148:151], v[178:181], v[78:81]
	v_mfma_f32_16x16x32_bf16 v[106:109], v[130:133], v[190:193], v[106:109]
	v_mfma_f32_16x16x32_bf16 v[74:77], v[148:151], v[190:193], v[74:77]
	v_mfma_f32_16x16x32_bf16 v[102:105], v[130:133], v[216:219], v[102:105]
	v_mfma_f32_16x16x32_bf16 v[70:73], v[148:151], v[216:219], v[70:73]
	v_mfma_f32_16x16x32_bf16 v[90:93], v[130:133], v[224:227], v[90:93]
	v_mfma_f32_16x16x32_bf16 v[58:61], v[148:151], v[224:227], v[58:61]
	v_mfma_f32_16x16x32_bf16 v[110:113], v[144:147], v[186:189], v[110:113]
	v_mfma_f32_16x16x32_bf16 v[78:81], v[152:155], v[186:189], v[78:81]
	v_mfma_f32_16x16x32_bf16 v[106:109], v[144:147], v[212:215], v[106:109]
	v_mfma_f32_16x16x32_bf16 v[74:77], v[152:155], v[212:215], v[74:77]
	v_mfma_f32_16x16x32_bf16 v[102:105], v[144:147], v[220:223], v[102:105]
	v_mfma_f32_16x16x32_bf16 v[70:73], v[152:155], v[220:223], v[70:73]
	v_mfma_f32_16x16x32_bf16 v[90:93], v[144:147], v[228:231], v[90:93]
	v_mfma_f32_16x16x32_bf16 v[58:61], v[152:155], v[228:231], v[58:61]
	v_mfma_f32_16x16x32_bf16 v[46:49], v[156:159], v[178:181], v[46:49]
	v_mfma_f32_16x16x32_bf16 v[14:17], v[170:173], v[178:181], v[14:17]
	v_mfma_f32_16x16x32_bf16 v[42:45], v[156:159], v[190:193], v[42:45]
	v_mfma_f32_16x16x32_bf16 v[10:13], v[170:173], v[190:193], v[10:13]
	v_mfma_f32_16x16x32_bf16 v[34:37], v[156:159], v[216:219], v[34:37]
	v_mfma_f32_16x16x32_bf16 v[6:9], v[170:173], v[216:219], v[6:9]
	v_mfma_f32_16x16x32_bf16 v[26:29], v[156:159], v[224:227], v[26:29]
	v_mfma_f32_16x16x32_bf16 v[2:5], v[170:173], v[224:227], v[2:5]
	v_mfma_f32_16x16x32_bf16 v[46:49], v[160:163], v[186:189], v[46:49]
	v_mfma_f32_16x16x32_bf16 v[14:17], v[174:177], v[186:189], v[14:17]
	v_mfma_f32_16x16x32_bf16 v[42:45], v[160:163], v[212:215], v[42:45]
	v_mfma_f32_16x16x32_bf16 v[10:13], v[174:177], v[212:215], v[10:13]
	v_mfma_f32_16x16x32_bf16 v[34:37], v[160:163], v[220:223], v[34:37]
	v_mfma_f32_16x16x32_bf16 v[6:9], v[174:177], v[220:223], v[6:9]
	v_mfma_f32_16x16x32_bf16 v[26:29], v[160:163], v[228:231], v[26:29]
	v_mfma_f32_16x16x32_bf16 v[2:5], v[174:177], v[228:231], v[2:5]
	s_barrier
	s_add_i32 s67, 0, 0x18000
	s_add_i32 s68, 0, 0x1c000
	v_add_u32_e32 v152, s67, v168
	v_add_u32_e32 v174, s68, v168
	ds_read_b128 v[130:133], v152
	ds_read_b128 v[144:147], v152 offset:1024
	ds_read_b128 v[148:151], v152 offset:2048
	ds_read_b128 v[152:155], v152 offset:3072
	ds_read_b128 v[156:159], v174
	ds_read_b128 v[160:163], v174 offset:1024
	ds_read_b128 v[170:173], v174 offset:2048
	ds_read_b128 v[174:177], v174 offset:3072
	s_add_u32 s14, s22, 0x160000
	s_addc_u32 s15, s23, 0
	s_mov_b32 m0, s37
	v_lshl_add_u64 v[236:237], s[14:15], 0, v[134:135]
	ds_read_b128 v[178:181], v169 offset:32768
	ds_read_b128 v[186:189], v169 offset:33792
	ds_read_b128 v[190:193], v169 offset:34816
	ds_read_b128 v[212:215], v169 offset:35840
	ds_read_b128 v[216:219], v169 offset:36864
	ds_read_b128 v[220:223], v169 offset:37888
	ds_read_b128 v[224:227], v169 offset:38912
	ds_read_b128 v[228:231], v169 offset:39936
	global_load_lds_dwordx4 v[236:237], off
	v_lshl_add_u64 v[236:237], s[14:15], 0, v[136:137]
	s_mov_b32 m0, s42
	s_nop 0
	global_load_lds_dwordx4 v[236:237], off
	s_waitcnt vmcnt(8)
	s_waitcnt lgkmcnt(0)
	s_barrier
	s_waitcnt lgkmcnt(0)
	v_mfma_f32_16x16x32_bf16 v[126:129], v[130:133], v[178:181], v[126:129]
	v_mfma_f32_16x16x32_bf16 v[98:101], v[148:151], v[178:181], v[98:101]
	v_mfma_f32_16x16x32_bf16 v[122:125], v[130:133], v[190:193], v[122:125]
	v_mfma_f32_16x16x32_bf16 v[94:97], v[148:151], v[190:193], v[94:97]
	v_mfma_f32_16x16x32_bf16 v[118:121], v[130:133], v[216:219], v[118:121]
	v_mfma_f32_16x16x32_bf16 v[86:89], v[148:151], v[216:219], v[86:89]
	v_mfma_f32_16x16x32_bf16 v[114:117], v[130:133], v[224:227], v[114:117]
	v_mfma_f32_16x16x32_bf16 v[82:85], v[148:151], v[224:227], v[82:85]
	v_mfma_f32_16x16x32_bf16 v[126:129], v[144:147], v[186:189], v[126:129]
	v_mfma_f32_16x16x32_bf16 v[98:101], v[152:155], v[186:189], v[98:101]
	v_mfma_f32_16x16x32_bf16 v[122:125], v[144:147], v[212:215], v[122:125]
	v_mfma_f32_16x16x32_bf16 v[94:97], v[152:155], v[212:215], v[94:97]
	v_mfma_f32_16x16x32_bf16 v[118:121], v[144:147], v[220:223], v[118:121]
	v_mfma_f32_16x16x32_bf16 v[86:89], v[152:155], v[220:223], v[86:89]
	v_mfma_f32_16x16x32_bf16 v[114:117], v[144:147], v[228:231], v[114:117]
	v_mfma_f32_16x16x32_bf16 v[82:85], v[152:155], v[228:231], v[82:85]
	v_mfma_f32_16x16x32_bf16 v[66:69], v[156:159], v[178:181], v[66:69]
	v_mfma_f32_16x16x32_bf16 v[38:41], v[170:173], v[178:181], v[38:41]
	v_mfma_f32_16x16x32_bf16 v[62:65], v[156:159], v[190:193], v[62:65]
	v_mfma_f32_16x16x32_bf16 v[30:33], v[170:173], v[190:193], v[30:33]
	v_mfma_f32_16x16x32_bf16 v[54:57], v[156:159], v[216:219], v[54:57]
	v_mfma_f32_16x16x32_bf16 v[22:25], v[170:173], v[216:219], v[22:25]
	v_mfma_f32_16x16x32_bf16 v[50:53], v[156:159], v[224:227], v[50:53]
	v_mfma_f32_16x16x32_bf16 v[18:21], v[170:173], v[224:227], v[18:21]
	v_mfma_f32_16x16x32_bf16 v[66:69], v[160:163], v[186:189], v[66:69]
	v_mfma_f32_16x16x32_bf16 v[38:41], v[174:177], v[186:189], v[38:41]
	v_mfma_f32_16x16x32_bf16 v[62:65], v[160:163], v[212:215], v[62:65]
	v_mfma_f32_16x16x32_bf16 v[30:33], v[174:177], v[212:215], v[30:33]
	v_mfma_f32_16x16x32_bf16 v[54:57], v[160:163], v[220:223], v[54:57]
	v_mfma_f32_16x16x32_bf16 v[22:25], v[174:177], v[220:223], v[22:25]
	v_mfma_f32_16x16x32_bf16 v[50:53], v[160:163], v[228:231], v[50:53]
	v_mfma_f32_16x16x32_bf16 v[18:21], v[174:177], v[228:231], v[18:21]
	s_barrier
	s_add_i32 s14, s67, s25
	v_lshl_add_u64 v[164:165], v[164:165], 0, s[16:17]
	s_mov_b32 m0, s14
	ds_read_b128 v[178:181], v169 offset:49152
	ds_read_b128 v[186:189], v169 offset:50176
	ds_read_b128 v[190:193], v169 offset:51200
	ds_read_b128 v[212:215], v169 offset:52224
	ds_read_b128 v[216:219], v169 offset:53248
	ds_read_b128 v[220:223], v169 offset:54272
	ds_read_b128 v[224:227], v169 offset:55296
	ds_read_b128 v[228:231], v169 offset:56320
	global_load_lds_dwordx4 v[164:165], off
	s_add_i32 m0, s14, 0x2000
	s_add_u32 s14, s20, 0xb0080
	v_lshl_add_u64 v[164:165], v[194:195], 0, s[16:17]
	s_addc_u32 s15, s21, 0
	s_add_i32 s20, s68, s25
	global_load_lds_dwordx4 v[164:165], off
	v_lshl_add_u64 v[164:165], s[14:15], 0, v[0:1]
	s_mov_b32 m0, s20
	s_nop 0
	global_load_lds_dwordx4 v[164:165], off
	v_lshl_add_u64 v[164:165], s[14:15], 0, v[138:139]
	s_add_i32 m0, s20, 0x2000
	s_nop 0
	global_load_lds_dwordx4 v[164:165], off
	v_lshl_add_u64 v[164:165], v[232:233], 0, s[16:17]
	s_mov_b32 m0, s48
	s_nop 0
	global_load_lds_dwordx4 v[164:165], off
	v_lshl_add_u64 v[164:165], v[234:235], 0, s[16:17]
	s_mov_b32 m0, s49
	s_nop 0
	global_load_lds_dwordx4 v[164:165], off
	s_waitcnt vmcnt(8)
	s_waitcnt lgkmcnt(0)
	s_barrier
	s_waitcnt lgkmcnt(0)
	v_mfma_f32_16x16x32_bf16 v[110:113], v[130:133], v[178:181], v[110:113]
	v_mfma_f32_16x16x32_bf16 v[78:81], v[148:151], v[178:181], v[78:81]
	v_mfma_f32_16x16x32_bf16 v[106:109], v[130:133], v[190:193], v[106:109]
	v_mfma_f32_16x16x32_bf16 v[74:77], v[148:151], v[190:193], v[74:77]
	v_mfma_f32_16x16x32_bf16 v[102:105], v[130:133], v[216:219], v[102:105]
	v_mfma_f32_16x16x32_bf16 v[70:73], v[148:151], v[216:219], v[70:73]
	v_mfma_f32_16x16x32_bf16 v[90:93], v[130:133], v[224:227], v[90:93]
	v_mfma_f32_16x16x32_bf16 v[58:61], v[148:151], v[224:227], v[58:61]
	v_mfma_f32_16x16x32_bf16 v[110:113], v[144:147], v[186:189], v[110:113]
	v_mfma_f32_16x16x32_bf16 v[78:81], v[152:155], v[186:189], v[78:81]
	v_mfma_f32_16x16x32_bf16 v[106:109], v[144:147], v[212:215], v[106:109]
	v_mfma_f32_16x16x32_bf16 v[74:77], v[152:155], v[212:215], v[74:77]
	v_mfma_f32_16x16x32_bf16 v[102:105], v[144:147], v[220:223], v[102:105]
	v_mfma_f32_16x16x32_bf16 v[70:73], v[152:155], v[220:223], v[70:73]
	v_mfma_f32_16x16x32_bf16 v[90:93], v[144:147], v[228:231], v[90:93]
	v_mfma_f32_16x16x32_bf16 v[58:61], v[152:155], v[228:231], v[58:61]
	v_mfma_f32_16x16x32_bf16 v[46:49], v[156:159], v[178:181], v[46:49]
	v_mfma_f32_16x16x32_bf16 v[14:17], v[170:173], v[178:181], v[14:17]
	v_mfma_f32_16x16x32_bf16 v[42:45], v[156:159], v[190:193], v[42:45]
	v_mfma_f32_16x16x32_bf16 v[10:13], v[170:173], v[190:193], v[10:13]
	v_mfma_f32_16x16x32_bf16 v[34:37], v[156:159], v[216:219], v[34:37]
	v_mfma_f32_16x16x32_bf16 v[6:9], v[170:173], v[216:219], v[6:9]
	v_mfma_f32_16x16x32_bf16 v[26:29], v[156:159], v[224:227], v[26:29]
	v_mfma_f32_16x16x32_bf16 v[2:5], v[170:173], v[224:227], v[2:5]
	v_mfma_f32_16x16x32_bf16 v[46:49], v[160:163], v[186:189], v[46:49]
	v_mfma_f32_16x16x32_bf16 v[14:17], v[174:177], v[186:189], v[14:17]
	v_mfma_f32_16x16x32_bf16 v[42:45], v[160:163], v[212:215], v[42:45]
	v_mfma_f32_16x16x32_bf16 v[10:13], v[174:177], v[212:215], v[10:13]
	v_mfma_f32_16x16x32_bf16 v[34:37], v[160:163], v[220:223], v[34:37]
	v_mfma_f32_16x16x32_bf16 v[6:9], v[174:177], v[220:223], v[6:9]
	v_mfma_f32_16x16x32_bf16 v[26:29], v[160:163], v[228:231], v[26:29]
	v_mfma_f32_16x16x32_bf16 v[2:5], v[174:177], v[228:231], v[2:5]
	s_barrier
	s_add_u32 s63, s63, 0x100
	s_addc_u32 s64, s64, 0
	s_cmp_ge_u32 s65, s45
	s_mov_b64 s[14:15], s[18:19]
	s_mov_b32 s20, s65
	s_cbranch_scc0 .LBB0_1215
	s_and_b64 vcc, exec, s[6:7]
	s_cbranch_vccz .LBB0_1218
	s_barrier
